# P2: u/bg full-line stores + v-tile butterfly by permlane swaps (on top of v-tile full-line stores)
# speedup vs baseline: 1.0060x; 1.0060x over previous
; __device__ __forceinline__ float gelu_tanh(float x) { const float u = 1.5957691216f * (x + 0.044715f * x * x * x); return x * __builtin_amdgcn_rcpf(1.f + __expf(-u)); }
; __device__ __forceinline__ void st_bf16x8(bf16_t* p, const f32x4 a, const f32x4 b) { uint4 o; o.x = cvt_pk_bf16(a[0], a[1]); o.y = cvt_pk_bf16(a[2], a[3]); o.z = cvt_pk_bf16(b[0], b[1]); o.w = cvt_pk_bf16(b[2], b[3]); *(uint4*)p = o; }
;     __device__ __forceinline__ void row(const f32x4 (&a)[2][2], int row, int pn, int wc, int fq) const {
;     ...
;             const int head = (pn - 2) * 4 + wc;
;             f32x4 g[2][2]; float ss = 0.f;
; #pragma unroll
;             for (int bj = 0; bj < 2; ++bj)
; #pragma unroll
;                 for (int n = 0; n < 2; ++n)
; #pragma unroll
;                     for (int j = 0; j < 4; ++j) { const float t = gelu_tanh(a[bj][n][j]); g[bj][n][j] = t; ss += t * t; }
;             ss += __shfl_xor(ss, 16); ss += __shfl_xor(ss, 32);
;             const float rs = rsqrtf(ss * (1.f / 64.f) + EPS);
; #pragma unroll
;             for (int bj = 0; bj < 2; ++bj) { const int d = head * 64 + bj * 32 + 8 * fq;
;                 const f32x4 v0 = g[bj][0] * rs * *(const f32x4*)(g_v + d), v1 = g[bj][1] * rs * *(const f32x4*)(g_v + d + 4);
;                 st_bf16x8(pV + (size_t)row * 512 + d, v0, v1);
.LBB0_218:
	s_andn2_b64 vcc, exec, s[0:1]
	s_cbranch_vccnz .LBB0_223
	v_mov_b32_e32 v190, 0x3d372713
	v_mov_b32_e32 v192, 0xbfcc422a
	v_mov_b32_e32 v194, 0x3fb8aa3b
	v_pk_mul_f32 v[128:129], v[124:125], v[190:191] op_sel_hi:[1,0]
	v_pk_mul_f32 v[132:133], v[126:127], v[190:191] op_sel_hi:[1,0]
	v_pk_mul_f32 v[158:159], v[120:121], v[190:191] op_sel_hi:[1,0]
	v_pk_mul_f32 v[160:161], v[122:123], v[190:191] op_sel_hi:[1,0]
	v_pk_mul_f32 v[162:163], v[116:117], v[190:191] op_sel_hi:[1,0]
	v_pk_mul_f32 v[164:165], v[118:119], v[190:191] op_sel_hi:[1,0]
	v_pk_mul_f32 v[166:167], v[112:113], v[190:191] op_sel_hi:[1,0]
	v_pk_mul_f32 v[168:169], v[114:115], v[190:191] op_sel_hi:[1,0]
	v_pk_mul_f32 v[128:129], v[124:125], v[128:129]
	v_pk_mul_f32 v[132:133], v[126:127], v[132:133]
	v_pk_mul_f32 v[158:159], v[120:121], v[158:159]
	v_pk_mul_f32 v[160:161], v[122:123], v[160:161]
	v_pk_mul_f32 v[162:163], v[116:117], v[162:163]
	v_pk_mul_f32 v[164:165], v[118:119], v[164:165]
	v_pk_mul_f32 v[166:167], v[112:113], v[166:167]
	v_pk_mul_f32 v[168:169], v[114:115], v[168:169]
	v_pk_fma_f32 v[128:129], v[124:125], v[128:129], v[124:125]
	v_pk_fma_f32 v[132:133], v[126:127], v[132:133], v[126:127]
	v_pk_fma_f32 v[158:159], v[120:121], v[158:159], v[120:121]
	v_pk_fma_f32 v[160:161], v[122:123], v[160:161], v[122:123]
	v_pk_fma_f32 v[162:163], v[116:117], v[162:163], v[116:117]
	v_pk_fma_f32 v[164:165], v[118:119], v[164:165], v[118:119]
	v_pk_fma_f32 v[166:167], v[112:113], v[166:167], v[112:113]
	v_pk_fma_f32 v[168:169], v[114:115], v[168:169], v[114:115]
	v_pk_mul_f32 v[128:129], v[128:129], v[192:193] op_sel_hi:[1,0]
	v_pk_mul_f32 v[132:133], v[132:133], v[192:193] op_sel_hi:[1,0]
	v_pk_mul_f32 v[158:159], v[158:159], v[192:193] op_sel_hi:[1,0]
	v_pk_mul_f32 v[160:161], v[160:161], v[192:193] op_sel_hi:[1,0]
	v_pk_mul_f32 v[162:163], v[162:163], v[192:193] op_sel_hi:[1,0]
	v_pk_mul_f32 v[164:165], v[164:165], v[192:193] op_sel_hi:[1,0]
	v_pk_mul_f32 v[166:167], v[166:167], v[192:193] op_sel_hi:[1,0]
	v_pk_mul_f32 v[168:169], v[168:169], v[192:193] op_sel_hi:[1,0]
	v_pk_mul_f32 v[128:129], v[128:129], v[194:195] op_sel_hi:[1,0]
	v_pk_mul_f32 v[132:133], v[132:133], v[194:195] op_sel_hi:[1,0]
	v_pk_mul_f32 v[158:159], v[158:159], v[194:195] op_sel_hi:[1,0]
	v_pk_mul_f32 v[160:161], v[160:161], v[194:195] op_sel_hi:[1,0]
	v_pk_mul_f32 v[162:163], v[162:163], v[194:195] op_sel_hi:[1,0]
	v_pk_mul_f32 v[164:165], v[164:165], v[194:195] op_sel_hi:[1,0]
	v_pk_mul_f32 v[166:167], v[166:167], v[194:195] op_sel_hi:[1,0]
	v_pk_mul_f32 v[168:169], v[168:169], v[194:195] op_sel_hi:[1,0]
	v_exp_f32_e32 v128, v128
	v_exp_f32_e32 v129, v129
	v_exp_f32_e32 v132, v132
	v_exp_f32_e32 v133, v133
	v_exp_f32_e32 v158, v158
	v_exp_f32_e32 v159, v159
	v_exp_f32_e32 v160, v160
	v_exp_f32_e32 v161, v161
	v_exp_f32_e32 v162, v162
	v_exp_f32_e32 v163, v163
	v_exp_f32_e32 v164, v164
	v_exp_f32_e32 v165, v165
	v_exp_f32_e32 v166, v166
	v_exp_f32_e32 v167, v167
	v_exp_f32_e32 v168, v168
	v_exp_f32_e32 v169, v169
	v_pk_add_f32 v[128:129], v[128:129], 1.0 op_sel_hi:[1,0]
	v_pk_add_f32 v[132:133], v[132:133], 1.0 op_sel_hi:[1,0]
	v_pk_add_f32 v[158:159], v[158:159], 1.0 op_sel_hi:[1,0]
	v_pk_add_f32 v[160:161], v[160:161], 1.0 op_sel_hi:[1,0]
	v_pk_add_f32 v[162:163], v[162:163], 1.0 op_sel_hi:[1,0]
	v_pk_add_f32 v[164:165], v[164:165], 1.0 op_sel_hi:[1,0]
	v_pk_add_f32 v[166:167], v[166:167], 1.0 op_sel_hi:[1,0]
	v_pk_add_f32 v[168:169], v[168:169], 1.0 op_sel_hi:[1,0]
	v_rcp_f32_e32 v128, v128
	v_rcp_f32_e32 v129, v129
	v_rcp_f32_e32 v132, v132
	v_rcp_f32_e32 v133, v133
	v_rcp_f32_e32 v158, v158
	v_rcp_f32_e32 v159, v159
	v_rcp_f32_e32 v160, v160
	v_rcp_f32_e32 v161, v161
	v_rcp_f32_e32 v162, v162
	v_rcp_f32_e32 v163, v163
	v_rcp_f32_e32 v164, v164
	v_rcp_f32_e32 v165, v165
	v_rcp_f32_e32 v166, v166
	v_rcp_f32_e32 v167, v167
	v_rcp_f32_e32 v168, v168
	v_rcp_f32_e32 v169, v169
	v_pk_mul_f32 v[128:129], v[124:125], v[128:129]
	v_pk_mul_f32 v[132:133], v[126:127], v[132:133]
	v_pk_mul_f32 v[158:159], v[120:121], v[158:159]
	v_pk_mul_f32 v[160:161], v[122:123], v[160:161]
	v_pk_mul_f32 v[162:163], v[116:117], v[162:163]
	v_pk_mul_f32 v[164:165], v[118:119], v[164:165]
	v_pk_mul_f32 v[166:167], v[112:113], v[166:167]
	v_pk_mul_f32 v[168:169], v[114:115], v[168:169]
	v_pk_mul_f32 v[130:131], v[128:129], v[128:129]
	v_pk_mul_f32 v[134:135], v[132:133], v[132:133]
	v_add_f32_e32 v130, v130, v131
	v_add_f32_e32 v130, v134, v130
	v_pk_mul_f32 v[170:171], v[158:159], v[158:159]
	v_add_f32_e32 v130, v135, v130
	v_add_f32_e32 v130, v170, v130
	v_pk_mul_f32 v[172:173], v[160:161], v[160:161]
	v_add_f32_e32 v130, v171, v130
	v_add_f32_e32 v130, v172, v130
	v_pk_mul_f32 v[174:175], v[162:163], v[162:163]
	v_add_f32_e32 v130, v173, v130
	v_add_f32_e32 v130, v130, v174
	v_pk_mul_f32 v[176:177], v[164:165], v[164:165]
	v_add_f32_e32 v130, v175, v130
	v_add_f32_e32 v130, v176, v130
	v_pk_mul_f32 v[178:179], v[166:167], v[166:167]
	v_add_f32_e32 v130, v177, v130
	v_add_f32_e32 v130, v178, v130
	v_pk_mul_f32 v[180:181], v[168:169], v[168:169]
	v_add_f32_e32 v130, v179, v130
	v_add_f32_e32 v130, v180, v130
	v_add_f32_e32 v130, v181, v130
	v_mov_b32_e32 v131, v130
	s_nop 1
	v_permlane16_swap_b32 v130, v131
	v_lshl_add_u64 v[180:181], v[140:141], 2, s[18:19]
	v_ashrrev_i32_e32 v157, 31, v156
	v_lshlrev_b64 v[174:175], 10, v[156:157]
	v_lshlrev_b32_e32 v172, 9, v156
	s_waitcnt lgkmcnt(0)
	v_add_f32_e32 v130, v130, v131
	v_mov_b32_e32 v131, v130
	s_nop 1
	v_permlane32_swap_b32 v130, v131
	v_mov_b32_e32 v173, v141
	v_cndmask_b32_e64 v157, 0, 1, s[10:11]
	v_cmp_ne_u32_e64 s[0:1], 1, v157
	s_waitcnt lgkmcnt(0)
	v_add_f32_e32 v130, v130, v131
	v_fmamk_f32 v130, v130, 0x3c800000, v188
	v_cmp_gt_f32_e32 vcc, s13, v130
	v_mul_f32_e32 v131, 0x4b800000, v130
	s_nop 0
	v_cndmask_b32_e32 v130, v130, v131, vcc
	v_rsq_f32_e32 v130, v130
	s_nop 0
	v_mul_f32_e32 v131, 0x45800000, v130
	v_cndmask_b32_e32 v170, v130, v131, vcc
	v_pk_mul_f32 v[176:177], v[128:129], v[170:171] op_sel_hi:[1,0]
	v_pk_mul_f32 v[178:179], v[132:133], v[170:171] op_sel_hi:[1,0]
	s_waitcnt vmcnt(0)
	v_mov_b64_e32 v[128:129], v[208:209]
	v_mov_b64_e32 v[130:131], v[210:211]
	v_mov_b64_e32 v[132:133], v[204:205]
	v_mov_b64_e32 v[134:135], v[206:207]
	v_pk_mul_f32 v[158:159], v[158:159], v[170:171] op_sel_hi:[1,0]
	v_pk_mul_f32 v[160:161], v[160:161], v[170:171] op_sel_hi:[1,0]
	s_andn2_b64 vcc, exec, s[10:11]
	v_pk_mul_f32 v[128:129], v[128:129], v[158:159]
	v_lshl_add_u64 v[158:159], s[46:47], 0, v[174:175]
	v_pk_mul_f32 v[134:135], v[134:135], v[178:179]
	v_pk_mul_f32 v[132:133], v[132:133], v[176:177]
	v_pk_mul_f32 v[130:131], v[130:131], v[160:161]
	v_lshl_add_u64 v[158:159], v[140:141], 1, v[158:159]
	v_lshl_add_u64 v[160:161], v[172:173], 2, s[56:57]
	v_cvt_pk_bf16_f32 v174, v132, v133
	v_cvt_pk_bf16_f32 v175, v134, v135
	v_cvt_pk_bf16_f32 v176, v128, v129
	v_cvt_pk_bf16_f32 v177, v130, v131
	v_mov_b64_e32 v[196:197], v[174:175]
	v_mov_b64_e32 v[198:199], v[176:177]
	s_cbranch_vccnz .LBB0_221
;     __device__ __forceinline__ void row(const f32x4 (&a)[2][2], int row, int pn, int wc, int fq) const {
;     ...
;                 if (row >= NP && row < NTOK) { float* o = out + O_VS + (size_t)(row - NP) * 512 + d; *(f32x4*)o = v0; *(f32x4*)(o + 4) = v1; } }
	v_lshl_add_u64 v[172:173], v[140:141], 2, v[160:161]
	v_lshl_add_u64 v[174:175], v[172:173], 0, s[70:71]
	v_add_co_u32_e32 v172, vcc, 0x2108000, v172
	s_nop 1
	v_addc_co_u32_e32 v173, vcc, 0, v173, vcc
	global_store_dwordx4 v[172:173], v[132:135], off
	global_store_dwordx4 v[174:175], v[128:131], off offset:16

; __device__ __forceinline__ float gelu_tanh(float x) { const float u = 1.5957691216f * (x + 0.044715f * x * x * x); return x * __builtin_amdgcn_rcpf(1.f + __expf(-u)); }
; __device__ __forceinline__ void st_bf16x8(bf16_t* p, const f32x4 a, const f32x4 b) { uint4 o; o.x = cvt_pk_bf16(a[0], a[1]); o.y = cvt_pk_bf16(a[2], a[3]); o.z = cvt_pk_bf16(b[0], b[1]); o.w = cvt_pk_bf16(b[2], b[3]); *(uint4*)p = o; }
;     __device__ __forceinline__ void row(const f32x4 (&a)[2][2], int row, int pn, int wc, int fq) const {
;     ...
;             const int head = (pn - 2) * 4 + wc;
;             f32x4 g[2][2]; float ss = 0.f;
; #pragma unroll
;             for (int bj = 0; bj < 2; ++bj)
; #pragma unroll
;                 for (int n = 0; n < 2; ++n)
; #pragma unroll
;                     for (int j = 0; j < 4; ++j) { const float t = gelu_tanh(a[bj][n][j]); g[bj][n][j] = t; ss += t * t; }
;             ss += __shfl_xor(ss, 16); ss += __shfl_xor(ss, 32);
;             const float rs = rsqrtf(ss * (1.f / 64.f) + EPS);
; #pragma unroll
;             for (int bj = 0; bj < 2; ++bj) { const int d = head * 64 + bj * 32 + 8 * fq;
;                 const f32x4 v0 = g[bj][0] * rs * *(const f32x4*)(g_v + d), v1 = g[bj][1] * rs * *(const f32x4*)(g_v + d + 4);
;                 st_bf16x8(pV + (size_t)row * 512 + d, v0, v1);
.LBB0_240:
	s_andn2_b64 vcc, exec, s[0:1]
	s_cbranch_vccnz .LBB0_245
	v_mov_b32_e32 v190, 0x3d372713
	v_mov_b32_e32 v192, 0xbfcc422a
	v_mov_b32_e32 v194, 0x3fb8aa3b
	v_pk_mul_f32 v[112:113], v[108:109], v[190:191] op_sel_hi:[1,0]
	v_pk_mul_f32 v[116:117], v[110:111], v[190:191] op_sel_hi:[1,0]
	v_pk_mul_f32 v[122:123], v[104:105], v[190:191] op_sel_hi:[1,0]
	v_pk_mul_f32 v[124:125], v[106:107], v[190:191] op_sel_hi:[1,0]
	v_pk_mul_f32 v[126:127], v[100:101], v[190:191] op_sel_hi:[1,0]
	v_pk_mul_f32 v[128:129], v[102:103], v[190:191] op_sel_hi:[1,0]
	v_pk_mul_f32 v[130:131], v[96:97], v[190:191] op_sel_hi:[1,0]
	v_pk_mul_f32 v[132:133], v[98:99], v[190:191] op_sel_hi:[1,0]
	v_pk_mul_f32 v[112:113], v[108:109], v[112:113]
	v_pk_mul_f32 v[116:117], v[110:111], v[116:117]
	v_pk_mul_f32 v[122:123], v[104:105], v[122:123]
	v_pk_mul_f32 v[124:125], v[106:107], v[124:125]
	v_pk_mul_f32 v[126:127], v[100:101], v[126:127]
	v_pk_mul_f32 v[128:129], v[102:103], v[128:129]
	v_pk_mul_f32 v[130:131], v[96:97], v[130:131]
	v_pk_mul_f32 v[132:133], v[98:99], v[132:133]
	v_pk_fma_f32 v[112:113], v[108:109], v[112:113], v[108:109]
	v_pk_fma_f32 v[116:117], v[110:111], v[116:117], v[110:111]
	v_pk_fma_f32 v[122:123], v[104:105], v[122:123], v[104:105]
	v_pk_fma_f32 v[124:125], v[106:107], v[124:125], v[106:107]
	v_pk_fma_f32 v[126:127], v[100:101], v[126:127], v[100:101]
	v_pk_fma_f32 v[128:129], v[102:103], v[128:129], v[102:103]
	v_pk_fma_f32 v[130:131], v[96:97], v[130:131], v[96:97]
	v_pk_fma_f32 v[132:133], v[98:99], v[132:133], v[98:99]
	v_pk_mul_f32 v[112:113], v[112:113], v[192:193] op_sel_hi:[1,0]
	v_pk_mul_f32 v[116:117], v[116:117], v[192:193] op_sel_hi:[1,0]
	v_pk_mul_f32 v[122:123], v[122:123], v[192:193] op_sel_hi:[1,0]
	v_pk_mul_f32 v[124:125], v[124:125], v[192:193] op_sel_hi:[1,0]
	v_pk_mul_f32 v[126:127], v[126:127], v[192:193] op_sel_hi:[1,0]
	v_pk_mul_f32 v[128:129], v[128:129], v[192:193] op_sel_hi:[1,0]
	v_pk_mul_f32 v[130:131], v[130:131], v[192:193] op_sel_hi:[1,0]
	v_pk_mul_f32 v[132:133], v[132:133], v[192:193] op_sel_hi:[1,0]
	v_pk_mul_f32 v[112:113], v[112:113], v[194:195] op_sel_hi:[1,0]
	v_pk_mul_f32 v[116:117], v[116:117], v[194:195] op_sel_hi:[1,0]
	v_pk_mul_f32 v[122:123], v[122:123], v[194:195] op_sel_hi:[1,0]
	v_pk_mul_f32 v[124:125], v[124:125], v[194:195] op_sel_hi:[1,0]
	v_pk_mul_f32 v[126:127], v[126:127], v[194:195] op_sel_hi:[1,0]
	v_pk_mul_f32 v[128:129], v[128:129], v[194:195] op_sel_hi:[1,0]
	v_pk_mul_f32 v[130:131], v[130:131], v[194:195] op_sel_hi:[1,0]
	v_pk_mul_f32 v[132:133], v[132:133], v[194:195] op_sel_hi:[1,0]
	v_exp_f32_e32 v112, v112
	v_exp_f32_e32 v113, v113
	v_exp_f32_e32 v116, v116
	v_exp_f32_e32 v117, v117
	v_exp_f32_e32 v122, v122
	v_exp_f32_e32 v123, v123
	v_exp_f32_e32 v124, v124
	v_exp_f32_e32 v125, v125
	v_exp_f32_e32 v126, v126
	v_exp_f32_e32 v127, v127
	v_exp_f32_e32 v128, v128
	v_exp_f32_e32 v129, v129
	v_exp_f32_e32 v130, v130
	v_exp_f32_e32 v131, v131
	v_exp_f32_e32 v132, v132
	v_exp_f32_e32 v133, v133
	v_pk_add_f32 v[112:113], v[112:113], 1.0 op_sel_hi:[1,0]
	v_pk_add_f32 v[116:117], v[116:117], 1.0 op_sel_hi:[1,0]
	v_pk_add_f32 v[122:123], v[122:123], 1.0 op_sel_hi:[1,0]
	v_pk_add_f32 v[124:125], v[124:125], 1.0 op_sel_hi:[1,0]
	v_pk_add_f32 v[126:127], v[126:127], 1.0 op_sel_hi:[1,0]
	v_pk_add_f32 v[128:129], v[128:129], 1.0 op_sel_hi:[1,0]
	v_pk_add_f32 v[130:131], v[130:131], 1.0 op_sel_hi:[1,0]
	v_pk_add_f32 v[132:133], v[132:133], 1.0 op_sel_hi:[1,0]
	v_rcp_f32_e32 v112, v112
	v_rcp_f32_e32 v113, v113
	v_rcp_f32_e32 v116, v116
	v_rcp_f32_e32 v117, v117
	v_rcp_f32_e32 v122, v122
	v_rcp_f32_e32 v123, v123
	v_rcp_f32_e32 v124, v124
	v_rcp_f32_e32 v125, v125
	v_rcp_f32_e32 v126, v126
	v_rcp_f32_e32 v127, v127
	v_rcp_f32_e32 v128, v128
	v_rcp_f32_e32 v129, v129
	v_rcp_f32_e32 v130, v130
	v_rcp_f32_e32 v131, v131
	v_rcp_f32_e32 v132, v132
	v_rcp_f32_e32 v133, v133
	v_pk_mul_f32 v[112:113], v[108:109], v[112:113]
	v_pk_mul_f32 v[116:117], v[110:111], v[116:117]
	v_pk_mul_f32 v[122:123], v[104:105], v[122:123]
	v_pk_mul_f32 v[124:125], v[106:107], v[124:125]
	v_pk_mul_f32 v[126:127], v[100:101], v[126:127]
	v_pk_mul_f32 v[128:129], v[102:103], v[128:129]
	v_pk_mul_f32 v[130:131], v[96:97], v[130:131]
	v_pk_mul_f32 v[132:133], v[98:99], v[132:133]
	v_pk_mul_f32 v[114:115], v[112:113], v[112:113]
	v_pk_mul_f32 v[118:119], v[116:117], v[116:117]
	v_add_f32_e32 v114, v114, v115
	v_add_f32_e32 v114, v118, v114
	v_pk_mul_f32 v[134:135], v[122:123], v[122:123]
	v_add_f32_e32 v114, v119, v114
	v_add_f32_e32 v114, v134, v114
	v_pk_mul_f32 v[158:159], v[124:125], v[124:125]
	v_add_f32_e32 v114, v135, v114
	v_add_f32_e32 v114, v158, v114
	v_pk_mul_f32 v[160:161], v[126:127], v[126:127]
	v_add_f32_e32 v114, v159, v114
	v_add_f32_e32 v114, v114, v160
	v_pk_mul_f32 v[162:163], v[128:129], v[128:129]
	v_add_f32_e32 v114, v161, v114
	v_add_f32_e32 v114, v162, v114
	v_pk_mul_f32 v[164:165], v[130:131], v[130:131]
	v_add_f32_e32 v114, v163, v114
	v_add_f32_e32 v114, v164, v114
	v_pk_mul_f32 v[166:167], v[132:133], v[132:133]
	v_add_f32_e32 v114, v165, v114
	v_add_f32_e32 v114, v166, v114
	v_add_f32_e32 v114, v167, v114
	v_mov_b32_e32 v115, v114
	s_nop 1
	v_permlane16_swap_b32 v114, v115
	v_lshl_add_u64 v[166:167], v[140:141], 2, s[18:19]
	v_ashrrev_i32_e32 v121, 31, v120
	v_lshlrev_b64 v[160:161], 10, v[120:121]
	v_lshlrev_b32_e32 v158, 9, v120
	s_waitcnt lgkmcnt(0)
	v_add_f32_e32 v114, v114, v115
	v_mov_b32_e32 v115, v114
	s_nop 1
	v_permlane32_swap_b32 v114, v115
	v_mov_b32_e32 v159, v141
	v_cndmask_b32_e64 v121, 0, 1, s[10:11]
	v_cmp_ne_u32_e64 s[0:1], 1, v121
	s_waitcnt lgkmcnt(0)
	v_add_f32_e32 v114, v114, v115
	v_fmamk_f32 v114, v114, 0x3c800000, v188
	v_cmp_gt_f32_e32 vcc, s13, v114
	v_mul_f32_e32 v115, 0x4b800000, v114
	s_nop 0
	v_cndmask_b32_e32 v114, v114, v115, vcc
	v_rsq_f32_e32 v114, v114
	s_nop 0
	v_mul_f32_e32 v115, 0x45800000, v114
	v_cndmask_b32_e32 v134, v114, v115, vcc
	v_pk_mul_f32 v[162:163], v[112:113], v[134:135] op_sel_hi:[1,0]
	v_pk_mul_f32 v[164:165], v[116:117], v[134:135] op_sel_hi:[1,0]
	v_mov_b64_e32 v[112:113], v[208:209]
	v_mov_b64_e32 v[114:115], v[210:211]
	v_mov_b64_e32 v[116:117], v[204:205]
	v_mov_b64_e32 v[118:119], v[206:207]
	v_pk_mul_f32 v[122:123], v[122:123], v[134:135] op_sel_hi:[1,0]
	v_pk_mul_f32 v[124:125], v[124:125], v[134:135] op_sel_hi:[1,0]
	s_andn2_b64 vcc, exec, s[10:11]
	v_pk_mul_f32 v[112:113], v[112:113], v[122:123]
	v_lshl_add_u64 v[122:123], s[46:47], 0, v[160:161]
	v_pk_mul_f32 v[118:119], v[118:119], v[164:165]
	v_pk_mul_f32 v[116:117], v[116:117], v[162:163]
	v_pk_mul_f32 v[114:115], v[114:115], v[124:125]
	v_lshl_add_u64 v[122:123], v[140:141], 1, v[122:123]
	v_lshl_add_u64 v[124:125], v[158:159], 2, s[56:57]
	v_cvt_pk_bf16_f32 v160, v116, v117
	v_cvt_pk_bf16_f32 v161, v118, v119
	v_cvt_pk_bf16_f32 v162, v112, v113
	v_cvt_pk_bf16_f32 v163, v114, v115
	v_mov_b64_e32 v[196:197], v[160:161]
	v_mov_b64_e32 v[198:199], v[162:163]
	s_cbranch_vccnz .LBB0_243
;     __device__ __forceinline__ void row(const f32x4 (&a)[2][2], int row, int pn, int wc, int fq) const {
;     ...
;                 if (row >= NP && row < NTOK) { float* o = out + O_VS + (size_t)(row - NP) * 512 + d; *(f32x4*)o = v0; *(f32x4*)(o + 4) = v1; } }
	v_lshl_add_u64 v[158:159], v[140:141], 2, v[124:125]
	v_lshl_add_u64 v[160:161], v[158:159], 0, s[70:71]
	v_add_co_u32_e32 v158, vcc, 0x2108000, v158
	s_nop 1
	v_addc_co_u32_e32 v159, vcc, 0, v159, vcc
	global_store_dwordx4 v[158:159], v[116:119], off
	global_store_dwordx4 v[160:161], v[112:115], off offset:16

; __device__ __forceinline__ float gelu_tanh(float x) { const float u = 1.5957691216f * (x + 0.044715f * x * x * x); return x * __builtin_amdgcn_rcpf(1.f + __expf(-u)); }
; __device__ __forceinline__ void st_bf16x8(bf16_t* p, const f32x4 a, const f32x4 b) { uint4 o; o.x = cvt_pk_bf16(a[0], a[1]); o.y = cvt_pk_bf16(a[2], a[3]); o.z = cvt_pk_bf16(b[0], b[1]); o.w = cvt_pk_bf16(b[2], b[3]); *(uint4*)p = o; }
;     __device__ __forceinline__ void row(const f32x4 (&a)[2][2], int row, int pn, int wc, int fq) const {
;     ...
;         } else if (pn < 4) {
;             const int head = (pn - 2) * 4 + wc;
;             f32x4 g[2][2]; float ss = 0.f;
; #pragma unroll
;             for (int bj = 0; bj < 2; ++bj)
; #pragma unroll
;                 for (int n = 0; n < 2; ++n)
; #pragma unroll
;                     for (int j = 0; j < 4; ++j) { const float t = gelu_tanh(a[bj][n][j]); g[bj][n][j] = t; ss += t * t; }
;             ss += __shfl_xor(ss, 16); ss += __shfl_xor(ss, 32);
;             const float rs = rsqrtf(ss * (1.f / 64.f) + EPS);
; #pragma unroll
;             for (int bj = 0; bj < 2; ++bj) { const int d = head * 64 + bj * 32 + 8 * fq;
;                 const f32x4 v0 = g[bj][0] * rs * *(const f32x4*)(g_v + d), v1 = g[bj][1] * rs * *(const f32x4*)(g_v + d + 4);
;                 st_bf16x8(pV + (size_t)row * 512 + d, v0, v1);
;                 if (row >= NP && row < NTOK) { float* o = out + O_VS + (size_t)(row - NP) * 512 + d; *(f32x4*)o = v0; *(f32x4*)(o + 4) = v1; } }
.LBB0_255:
	s_andn2_b64 vcc, exec, s[0:1]
	s_cbranch_vccnz .LBB0_260
	v_mov_b32_e32 v190, 0x3d372713
	v_mov_b32_e32 v192, 0xbfcc422a
	v_mov_b32_e32 v194, 0x3fb8aa3b
	v_pk_mul_f32 v[96:97], v[92:93], v[190:191] op_sel_hi:[1,0]
	v_pk_mul_f32 v[100:101], v[94:95], v[190:191] op_sel_hi:[1,0]
	v_pk_mul_f32 v[106:107], v[88:89], v[190:191] op_sel_hi:[1,0]
	v_pk_mul_f32 v[108:109], v[90:91], v[190:191] op_sel_hi:[1,0]
	v_pk_mul_f32 v[110:111], v[84:85], v[190:191] op_sel_hi:[1,0]
	v_pk_mul_f32 v[112:113], v[86:87], v[190:191] op_sel_hi:[1,0]
	v_pk_mul_f32 v[114:115], v[80:81], v[190:191] op_sel_hi:[1,0]
	v_pk_mul_f32 v[116:117], v[82:83], v[190:191] op_sel_hi:[1,0]
	v_pk_mul_f32 v[96:97], v[92:93], v[96:97]
	v_pk_mul_f32 v[100:101], v[94:95], v[100:101]
	v_pk_mul_f32 v[106:107], v[88:89], v[106:107]
	v_pk_mul_f32 v[108:109], v[90:91], v[108:109]
	v_pk_mul_f32 v[110:111], v[84:85], v[110:111]
	v_pk_mul_f32 v[112:113], v[86:87], v[112:113]
	v_pk_mul_f32 v[114:115], v[80:81], v[114:115]
	v_pk_mul_f32 v[116:117], v[82:83], v[116:117]
	v_pk_fma_f32 v[96:97], v[92:93], v[96:97], v[92:93]
	v_pk_fma_f32 v[100:101], v[94:95], v[100:101], v[94:95]
	v_pk_fma_f32 v[106:107], v[88:89], v[106:107], v[88:89]
	v_pk_fma_f32 v[108:109], v[90:91], v[108:109], v[90:91]
	v_pk_fma_f32 v[110:111], v[84:85], v[110:111], v[84:85]
	v_pk_fma_f32 v[112:113], v[86:87], v[112:113], v[86:87]
	v_pk_fma_f32 v[114:115], v[80:81], v[114:115], v[80:81]
	v_pk_fma_f32 v[116:117], v[82:83], v[116:117], v[82:83]
	v_pk_mul_f32 v[96:97], v[96:97], v[192:193] op_sel_hi:[1,0]
	v_pk_mul_f32 v[100:101], v[100:101], v[192:193] op_sel_hi:[1,0]
	v_pk_mul_f32 v[106:107], v[106:107], v[192:193] op_sel_hi:[1,0]
	v_pk_mul_f32 v[108:109], v[108:109], v[192:193] op_sel_hi:[1,0]
	v_pk_mul_f32 v[110:111], v[110:111], v[192:193] op_sel_hi:[1,0]
	v_pk_mul_f32 v[112:113], v[112:113], v[192:193] op_sel_hi:[1,0]
	v_pk_mul_f32 v[114:115], v[114:115], v[192:193] op_sel_hi:[1,0]
	v_pk_mul_f32 v[116:117], v[116:117], v[192:193] op_sel_hi:[1,0]
	v_pk_mul_f32 v[96:97], v[96:97], v[194:195] op_sel_hi:[1,0]
	v_pk_mul_f32 v[100:101], v[100:101], v[194:195] op_sel_hi:[1,0]
	v_pk_mul_f32 v[106:107], v[106:107], v[194:195] op_sel_hi:[1,0]
	v_pk_mul_f32 v[108:109], v[108:109], v[194:195] op_sel_hi:[1,0]
	v_pk_mul_f32 v[110:111], v[110:111], v[194:195] op_sel_hi:[1,0]
	v_pk_mul_f32 v[112:113], v[112:113], v[194:195] op_sel_hi:[1,0]
	v_pk_mul_f32 v[114:115], v[114:115], v[194:195] op_sel_hi:[1,0]
	v_pk_mul_f32 v[116:117], v[116:117], v[194:195] op_sel_hi:[1,0]
	v_exp_f32_e32 v96, v96
	v_exp_f32_e32 v97, v97
	v_exp_f32_e32 v100, v100
	v_exp_f32_e32 v101, v101
	v_exp_f32_e32 v106, v106
	v_exp_f32_e32 v107, v107
	v_exp_f32_e32 v108, v108
	v_exp_f32_e32 v109, v109
	v_exp_f32_e32 v110, v110
	v_exp_f32_e32 v111, v111
	v_exp_f32_e32 v112, v112
	v_exp_f32_e32 v113, v113
	v_exp_f32_e32 v114, v114
	v_exp_f32_e32 v115, v115
	v_exp_f32_e32 v116, v116
	v_exp_f32_e32 v117, v117
	v_pk_add_f32 v[96:97], v[96:97], 1.0 op_sel_hi:[1,0]
	v_pk_add_f32 v[100:101], v[100:101], 1.0 op_sel_hi:[1,0]
	v_pk_add_f32 v[106:107], v[106:107], 1.0 op_sel_hi:[1,0]
	v_pk_add_f32 v[108:109], v[108:109], 1.0 op_sel_hi:[1,0]
	v_pk_add_f32 v[110:111], v[110:111], 1.0 op_sel_hi:[1,0]
	v_pk_add_f32 v[112:113], v[112:113], 1.0 op_sel_hi:[1,0]
	v_pk_add_f32 v[114:115], v[114:115], 1.0 op_sel_hi:[1,0]
	v_pk_add_f32 v[116:117], v[116:117], 1.0 op_sel_hi:[1,0]
	v_rcp_f32_e32 v96, v96
	v_rcp_f32_e32 v97, v97
	v_rcp_f32_e32 v100, v100
	v_rcp_f32_e32 v101, v101
	v_rcp_f32_e32 v106, v106
	v_rcp_f32_e32 v107, v107
	v_rcp_f32_e32 v108, v108
	v_rcp_f32_e32 v109, v109
	v_rcp_f32_e32 v110, v110
	v_rcp_f32_e32 v111, v111
	v_rcp_f32_e32 v112, v112
	v_rcp_f32_e32 v113, v113
	v_rcp_f32_e32 v114, v114
	v_rcp_f32_e32 v115, v115
	v_rcp_f32_e32 v116, v116
	v_rcp_f32_e32 v117, v117
	v_pk_mul_f32 v[96:97], v[92:93], v[96:97]
	v_pk_mul_f32 v[100:101], v[94:95], v[100:101]
	v_pk_mul_f32 v[106:107], v[88:89], v[106:107]
	v_pk_mul_f32 v[108:109], v[90:91], v[108:109]
	v_pk_mul_f32 v[110:111], v[84:85], v[110:111]
	v_pk_mul_f32 v[112:113], v[86:87], v[112:113]
	v_pk_mul_f32 v[114:115], v[80:81], v[114:115]
	v_pk_mul_f32 v[116:117], v[82:83], v[116:117]
	v_pk_mul_f32 v[98:99], v[96:97], v[96:97]
	v_pk_mul_f32 v[102:103], v[100:101], v[100:101]
	v_add_f32_e32 v98, v98, v99
	v_add_f32_e32 v98, v102, v98
	v_pk_mul_f32 v[118:119], v[106:107], v[106:107]
	v_add_f32_e32 v98, v103, v98
	v_add_f32_e32 v98, v118, v98
	v_pk_mul_f32 v[120:121], v[108:109], v[108:109]
	v_add_f32_e32 v98, v119, v98
	v_add_f32_e32 v98, v120, v98
	v_pk_mul_f32 v[122:123], v[110:111], v[110:111]
	v_add_f32_e32 v98, v121, v98
	v_add_f32_e32 v98, v98, v122
	v_pk_mul_f32 v[124:125], v[112:113], v[112:113]
	v_add_f32_e32 v98, v123, v98
	v_add_f32_e32 v98, v124, v98
	v_pk_mul_f32 v[126:127], v[114:115], v[114:115]
	v_add_f32_e32 v98, v125, v98
	v_add_f32_e32 v98, v126, v98
	v_pk_mul_f32 v[128:129], v[116:117], v[116:117]
	v_add_f32_e32 v98, v127, v98
	v_add_f32_e32 v98, v128, v98
	v_add_f32_e32 v98, v129, v98
	v_mov_b32_e32 v99, v98
	s_nop 1
	v_permlane16_swap_b32 v98, v99
	v_lshl_add_u64 v[128:129], v[140:141], 2, s[18:19]
	v_ashrrev_i32_e32 v105, 31, v104
	v_lshlrev_b64 v[122:123], 10, v[104:105]
	v_lshlrev_b32_e32 v120, 9, v104
	s_waitcnt lgkmcnt(0)
	v_add_f32_e32 v98, v98, v99
	v_mov_b32_e32 v99, v98
	s_nop 1
	v_permlane32_swap_b32 v98, v99
	v_mov_b32_e32 v121, v141
	v_cndmask_b32_e64 v105, 0, 1, s[10:11]
	v_cmp_ne_u32_e64 s[0:1], 1, v105
	s_waitcnt lgkmcnt(0)
	v_add_f32_e32 v98, v98, v99
	v_fmamk_f32 v98, v98, 0x3c800000, v188
	v_cmp_gt_f32_e32 vcc, s13, v98
	v_mul_f32_e32 v99, 0x4b800000, v98
	s_nop 0
	v_cndmask_b32_e32 v98, v98, v99, vcc
	v_rsq_f32_e32 v98, v98
	s_nop 0
	v_mul_f32_e32 v99, 0x45800000, v98
	v_cndmask_b32_e32 v118, v98, v99, vcc
	v_pk_mul_f32 v[124:125], v[96:97], v[118:119] op_sel_hi:[1,0]
	v_pk_mul_f32 v[126:127], v[100:101], v[118:119] op_sel_hi:[1,0]
	v_mov_b64_e32 v[96:97], v[208:209]
	v_mov_b64_e32 v[98:99], v[210:211]
	v_mov_b64_e32 v[100:101], v[204:205]
	v_mov_b64_e32 v[102:103], v[206:207]
	v_pk_mul_f32 v[106:107], v[106:107], v[118:119] op_sel_hi:[1,0]
	v_pk_mul_f32 v[108:109], v[108:109], v[118:119] op_sel_hi:[1,0]
	s_andn2_b64 vcc, exec, s[10:11]
	v_pk_mul_f32 v[96:97], v[96:97], v[106:107]
	v_lshl_add_u64 v[106:107], s[46:47], 0, v[122:123]
	v_pk_mul_f32 v[102:103], v[102:103], v[126:127]
	v_pk_mul_f32 v[100:101], v[100:101], v[124:125]
	v_pk_mul_f32 v[98:99], v[98:99], v[108:109]
	v_lshl_add_u64 v[106:107], v[140:141], 1, v[106:107]
	v_lshl_add_u64 v[108:109], v[120:121], 2, s[56:57]
	v_cvt_pk_bf16_f32 v122, v100, v101
	v_cvt_pk_bf16_f32 v123, v102, v103
	v_cvt_pk_bf16_f32 v124, v96, v97
	v_cvt_pk_bf16_f32 v125, v98, v99
	v_mov_b64_e32 v[196:197], v[122:123]
	v_mov_b64_e32 v[198:199], v[124:125]
	s_cbranch_vccnz .LBB0_258
; __device__ __forceinline__ void st_bf16x8(bf16_t* p, const f32x4 a, const f32x4 b) { uint4 o; o.x = cvt_pk_bf16(a[0], a[1]); o.y = cvt_pk_bf16(a[2], a[3]); o.z = cvt_pk_bf16(b[0], b[1]); o.w = cvt_pk_bf16(b[2], b[3]); *(uint4*)p = o; }
;     __device__ __forceinline__ void row(const f32x4 (&a)[2][2], int row, int pn, int wc, int fq) const {
;     ...
;                 const f32x4 v0 = g[bj][0] * rs * *(const f32x4*)(g_v + d), v1 = g[bj][1] * rs * *(const f32x4*)(g_v + d + 4);
;                 st_bf16x8(pV + (size_t)row * 512 + d, v0, v1);
;                 if (row >= NP && row < NTOK) { float* o = out + O_VS + (size_t)(row - NP) * 512 + d; *(f32x4*)o = v0; *(f32x4*)(o + 4) = v1; } }
	v_lshl_add_u64 v[120:121], v[140:141], 2, v[108:109]
	v_lshl_add_u64 v[122:123], v[120:121], 0, s[70:71]
	v_add_co_u32_e32 v120, vcc, 0x2108000, v120
	s_nop 1
	v_addc_co_u32_e32 v121, vcc, 0, v121, vcc
	global_store_dwordx4 v[120:121], v[100:103], off
	global_store_dwordx4 v[122:123], v[96:99], off offset:16

; __device__ __forceinline__ float gelu_tanh(float x) { const float u = 1.5957691216f * (x + 0.044715f * x * x * x); return x * __builtin_amdgcn_rcpf(1.f + __expf(-u)); }
; __device__ __forceinline__ void st_bf16x8(bf16_t* p, const f32x4 a, const f32x4 b) { uint4 o; o.x = cvt_pk_bf16(a[0], a[1]); o.y = cvt_pk_bf16(a[2], a[3]); o.z = cvt_pk_bf16(b[0], b[1]); o.w = cvt_pk_bf16(b[2], b[3]); *(uint4*)p = o; }
;     __device__ __forceinline__ void row(const f32x4 (&a)[2][2], int row, int pn, int wc, int fq) const {
;     ...
;         } else if (pn < 4) {
;             const int head = (pn - 2) * 4 + wc;
;             f32x4 g[2][2]; float ss = 0.f;
; #pragma unroll
;             for (int bj = 0; bj < 2; ++bj)
; #pragma unroll
;                 for (int n = 0; n < 2; ++n)
; #pragma unroll
;                     for (int j = 0; j < 4; ++j) { const float t = gelu_tanh(a[bj][n][j]); g[bj][n][j] = t; ss += t * t; }
;             ss += __shfl_xor(ss, 16); ss += __shfl_xor(ss, 32);
;             const float rs = rsqrtf(ss * (1.f / 64.f) + EPS);
; #pragma unroll
;             for (int bj = 0; bj < 2; ++bj) { const int d = head * 64 + bj * 32 + 8 * fq;
;                 const f32x4 v0 = g[bj][0] * rs * *(const f32x4*)(g_v + d), v1 = g[bj][1] * rs * *(const f32x4*)(g_v + d + 4);
;                 st_bf16x8(pV + (size_t)row * 512 + d, v0, v1);
;                 if (row >= NP && row < NTOK) { float* o = out + O_VS + (size_t)(row - NP) * 512 + d; *(f32x4*)o = v0; *(f32x4*)(o + 4) = v1; } }
.LBB0_272:
	s_and_b64 vcc, exec, s[0:1]
	s_cbranch_vccz .LBB0_277
	v_mov_b32_e32 v190, 0x3d372713
	v_mov_b32_e32 v192, 0xbfcc422a
	v_mov_b32_e32 v194, 0x3fb8aa3b
	v_pk_mul_f32 v[80:81], v[76:77], v[190:191] op_sel_hi:[1,0]
	v_pk_mul_f32 v[84:85], v[78:79], v[190:191] op_sel_hi:[1,0]
	v_pk_mul_f32 v[90:91], v[72:73], v[190:191] op_sel_hi:[1,0]
	v_pk_mul_f32 v[92:93], v[74:75], v[190:191] op_sel_hi:[1,0]
	v_pk_mul_f32 v[94:95], v[68:69], v[190:191] op_sel_hi:[1,0]
	v_pk_mul_f32 v[96:97], v[70:71], v[190:191] op_sel_hi:[1,0]
	v_pk_mul_f32 v[98:99], v[64:65], v[190:191] op_sel_hi:[1,0]
	v_pk_mul_f32 v[100:101], v[66:67], v[190:191] op_sel_hi:[1,0]
	v_pk_mul_f32 v[80:81], v[76:77], v[80:81]
	v_pk_mul_f32 v[84:85], v[78:79], v[84:85]
	v_pk_mul_f32 v[90:91], v[72:73], v[90:91]
	v_pk_mul_f32 v[92:93], v[74:75], v[92:93]
	v_pk_mul_f32 v[94:95], v[68:69], v[94:95]
	v_pk_mul_f32 v[96:97], v[70:71], v[96:97]
	v_pk_mul_f32 v[98:99], v[64:65], v[98:99]
	v_pk_mul_f32 v[100:101], v[66:67], v[100:101]
	v_pk_fma_f32 v[80:81], v[76:77], v[80:81], v[76:77]
	v_pk_fma_f32 v[84:85], v[78:79], v[84:85], v[78:79]
	v_pk_fma_f32 v[90:91], v[72:73], v[90:91], v[72:73]
	v_pk_fma_f32 v[92:93], v[74:75], v[92:93], v[74:75]
	v_pk_fma_f32 v[94:95], v[68:69], v[94:95], v[68:69]
	v_pk_fma_f32 v[96:97], v[70:71], v[96:97], v[70:71]
	v_pk_fma_f32 v[98:99], v[64:65], v[98:99], v[64:65]
	v_pk_fma_f32 v[100:101], v[66:67], v[100:101], v[66:67]
	v_pk_mul_f32 v[80:81], v[80:81], v[192:193] op_sel_hi:[1,0]
	v_pk_mul_f32 v[84:85], v[84:85], v[192:193] op_sel_hi:[1,0]
	v_pk_mul_f32 v[90:91], v[90:91], v[192:193] op_sel_hi:[1,0]
	v_pk_mul_f32 v[92:93], v[92:93], v[192:193] op_sel_hi:[1,0]
	v_pk_mul_f32 v[94:95], v[94:95], v[192:193] op_sel_hi:[1,0]
	v_pk_mul_f32 v[96:97], v[96:97], v[192:193] op_sel_hi:[1,0]
	v_pk_mul_f32 v[98:99], v[98:99], v[192:193] op_sel_hi:[1,0]
	v_pk_mul_f32 v[100:101], v[100:101], v[192:193] op_sel_hi:[1,0]
	v_pk_mul_f32 v[80:81], v[80:81], v[194:195] op_sel_hi:[1,0]
	v_pk_mul_f32 v[84:85], v[84:85], v[194:195] op_sel_hi:[1,0]
	v_pk_mul_f32 v[90:91], v[90:91], v[194:195] op_sel_hi:[1,0]
	v_pk_mul_f32 v[92:93], v[92:93], v[194:195] op_sel_hi:[1,0]
	v_pk_mul_f32 v[94:95], v[94:95], v[194:195] op_sel_hi:[1,0]
	v_pk_mul_f32 v[96:97], v[96:97], v[194:195] op_sel_hi:[1,0]
	v_pk_mul_f32 v[98:99], v[98:99], v[194:195] op_sel_hi:[1,0]
	v_pk_mul_f32 v[100:101], v[100:101], v[194:195] op_sel_hi:[1,0]
	v_exp_f32_e32 v80, v80
	v_exp_f32_e32 v81, v81
	v_exp_f32_e32 v84, v84
	v_exp_f32_e32 v85, v85
	v_exp_f32_e32 v90, v90
	v_exp_f32_e32 v91, v91
	v_exp_f32_e32 v92, v92
	v_exp_f32_e32 v93, v93
	v_exp_f32_e32 v94, v94
	v_exp_f32_e32 v95, v95
	v_exp_f32_e32 v96, v96
	v_exp_f32_e32 v97, v97
	v_exp_f32_e32 v98, v98
	v_exp_f32_e32 v99, v99
	v_exp_f32_e32 v100, v100
	v_exp_f32_e32 v101, v101
	v_pk_add_f32 v[80:81], v[80:81], 1.0 op_sel_hi:[1,0]
	v_pk_add_f32 v[84:85], v[84:85], 1.0 op_sel_hi:[1,0]
	v_pk_add_f32 v[90:91], v[90:91], 1.0 op_sel_hi:[1,0]
	v_pk_add_f32 v[92:93], v[92:93], 1.0 op_sel_hi:[1,0]
	v_pk_add_f32 v[94:95], v[94:95], 1.0 op_sel_hi:[1,0]
	v_pk_add_f32 v[96:97], v[96:97], 1.0 op_sel_hi:[1,0]
	v_pk_add_f32 v[98:99], v[98:99], 1.0 op_sel_hi:[1,0]
	v_pk_add_f32 v[100:101], v[100:101], 1.0 op_sel_hi:[1,0]
	v_rcp_f32_e32 v80, v80
	v_rcp_f32_e32 v81, v81
	v_rcp_f32_e32 v84, v84
	v_rcp_f32_e32 v85, v85
	v_rcp_f32_e32 v90, v90
	v_rcp_f32_e32 v91, v91
	v_rcp_f32_e32 v92, v92
	v_rcp_f32_e32 v93, v93
	v_rcp_f32_e32 v94, v94
	v_rcp_f32_e32 v95, v95
	v_rcp_f32_e32 v96, v96
	v_rcp_f32_e32 v97, v97
	v_rcp_f32_e32 v98, v98
	v_rcp_f32_e32 v99, v99
	v_rcp_f32_e32 v100, v100
	v_rcp_f32_e32 v101, v101
	v_pk_mul_f32 v[80:81], v[76:77], v[80:81]
	v_pk_mul_f32 v[84:85], v[78:79], v[84:85]
	v_pk_mul_f32 v[90:91], v[72:73], v[90:91]
	v_pk_mul_f32 v[92:93], v[74:75], v[92:93]
	v_pk_mul_f32 v[94:95], v[68:69], v[94:95]
	v_pk_mul_f32 v[96:97], v[70:71], v[96:97]
	v_pk_mul_f32 v[98:99], v[64:65], v[98:99]
	v_pk_mul_f32 v[100:101], v[66:67], v[100:101]
	v_pk_mul_f32 v[82:83], v[80:81], v[80:81]
	v_pk_mul_f32 v[86:87], v[84:85], v[84:85]
	v_add_f32_e32 v82, v82, v83
	v_add_f32_e32 v82, v86, v82
	v_pk_mul_f32 v[102:103], v[90:91], v[90:91]
	v_add_f32_e32 v82, v87, v82
	v_add_f32_e32 v82, v102, v82
	v_pk_mul_f32 v[104:105], v[92:93], v[92:93]
	v_add_f32_e32 v82, v103, v82
	v_add_f32_e32 v82, v104, v82
	v_pk_mul_f32 v[106:107], v[94:95], v[94:95]
	v_add_f32_e32 v82, v105, v82
	v_add_f32_e32 v82, v82, v106
	v_pk_mul_f32 v[108:109], v[96:97], v[96:97]
	v_add_f32_e32 v82, v107, v82
	v_add_f32_e32 v82, v108, v82
	v_pk_mul_f32 v[110:111], v[98:99], v[98:99]
	v_add_f32_e32 v82, v109, v82
	v_add_f32_e32 v82, v110, v82
	v_pk_mul_f32 v[112:113], v[100:101], v[100:101]
	v_add_f32_e32 v82, v111, v82
	v_add_f32_e32 v82, v112, v82
	v_add_f32_e32 v82, v113, v82
	v_mov_b32_e32 v83, v82
	s_nop 1
	v_permlane16_swap_b32 v82, v83
	v_lshl_add_u64 v[112:113], v[140:141], 2, s[18:19]
	v_ashrrev_i32_e32 v89, 31, v88
	v_lshlrev_b64 v[106:107], 10, v[88:89]
	v_lshlrev_b32_e32 v104, 9, v88
	s_waitcnt lgkmcnt(0)
	v_add_f32_e32 v82, v82, v83
	v_mov_b32_e32 v83, v82
	s_nop 1
	v_permlane32_swap_b32 v82, v83
	v_mov_b32_e32 v105, v141
	v_cndmask_b32_e64 v89, 0, 1, s[10:11]
	v_cmp_ne_u32_e64 s[0:1], 1, v89
	s_waitcnt lgkmcnt(0)
	v_add_f32_e32 v82, v82, v83
	v_fmamk_f32 v82, v82, 0x3c800000, v188
	v_cmp_gt_f32_e32 vcc, s13, v82
	v_mul_f32_e32 v83, 0x4b800000, v82
	s_nop 0
	v_cndmask_b32_e32 v82, v82, v83, vcc
	v_rsq_f32_e32 v82, v82
	s_nop 0
	v_mul_f32_e32 v83, 0x45800000, v82
	v_cndmask_b32_e32 v102, v82, v83, vcc
	v_pk_mul_f32 v[108:109], v[80:81], v[102:103] op_sel_hi:[1,0]
	v_pk_mul_f32 v[110:111], v[84:85], v[102:103] op_sel_hi:[1,0]
	v_mov_b64_e32 v[80:81], v[208:209]
	v_mov_b64_e32 v[82:83], v[210:211]
	v_mov_b64_e32 v[84:85], v[204:205]
	v_mov_b64_e32 v[86:87], v[206:207]
	v_pk_mul_f32 v[90:91], v[90:91], v[102:103] op_sel_hi:[1,0]
	v_pk_mul_f32 v[92:93], v[92:93], v[102:103] op_sel_hi:[1,0]
	s_andn2_b64 vcc, exec, s[10:11]
	v_pk_mul_f32 v[80:81], v[80:81], v[90:91]
	v_lshl_add_u64 v[90:91], s[46:47], 0, v[106:107]
	v_pk_mul_f32 v[86:87], v[86:87], v[110:111]
	v_pk_mul_f32 v[84:85], v[84:85], v[108:109]
	v_pk_mul_f32 v[82:83], v[82:83], v[92:93]
	v_lshl_add_u64 v[90:91], v[140:141], 1, v[90:91]
	v_lshl_add_u64 v[92:93], v[104:105], 2, s[56:57]
	v_cvt_pk_bf16_f32 v106, v84, v85
	v_cvt_pk_bf16_f32 v107, v86, v87
	v_cvt_pk_bf16_f32 v108, v80, v81
	v_cvt_pk_bf16_f32 v109, v82, v83
	v_mov_b64_e32 v[196:197], v[106:107]
	v_mov_b64_e32 v[198:199], v[108:109]
	s_cbranch_vccnz .LBB0_275
	v_lshl_add_u64 v[104:105], v[140:141], 2, v[92:93]
	v_lshl_add_u64 v[106:107], v[104:105], 0, s[70:71]
	v_add_co_u32_e32 v104, vcc, 0x2108000, v104
	s_nop 1
	v_addc_co_u32_e32 v105, vcc, 0, v105, vcc
	global_store_dwordx4 v[104:105], v[84:87], off
	global_store_dwordx4 v[106:107], v[80:83], off offset:16

; __device__ __forceinline__ float gelu_tanh(float x) { const float u = 1.5957691216f * (x + 0.044715f * x * x * x); return x * __builtin_amdgcn_rcpf(1.f + __expf(-u)); }
; __device__ __forceinline__ void st_bf16x8(bf16_t* p, const f32x4 a, const f32x4 b) { uint4 o; o.x = cvt_pk_bf16(a[0], a[1]); o.y = cvt_pk_bf16(a[2], a[3]); o.z = cvt_pk_bf16(b[0], b[1]); o.w = cvt_pk_bf16(b[2], b[3]); *(uint4*)p = o; }
;     __device__ __forceinline__ void row(const f32x4 (&a)[2][2], int row, int pn, int wc, int fq) const {
;     ...
;         } else if (pn < 4) {
;             const int head = (pn - 2) * 4 + wc;
;             f32x4 g[2][2]; float ss = 0.f;
; #pragma unroll
;             for (int bj = 0; bj < 2; ++bj)
; #pragma unroll
;                 for (int n = 0; n < 2; ++n)
; #pragma unroll
;                     for (int j = 0; j < 4; ++j) { const float t = gelu_tanh(a[bj][n][j]); g[bj][n][j] = t; ss += t * t; }
;             ss += __shfl_xor(ss, 16); ss += __shfl_xor(ss, 32);
;             const float rs = rsqrtf(ss * (1.f / 64.f) + EPS);
; #pragma unroll
;             for (int bj = 0; bj < 2; ++bj) { const int d = head * 64 + bj * 32 + 8 * fq;
;                 const f32x4 v0 = g[bj][0] * rs * *(const f32x4*)(g_v + d), v1 = g[bj][1] * rs * *(const f32x4*)(g_v + d + 4);
;                 st_bf16x8(pV + (size_t)row * 512 + d, v0, v1);
;                 if (row >= NP && row < NTOK) { float* o = out + O_VS + (size_t)(row - NP) * 512 + d; *(f32x4*)o = v0; *(f32x4*)(o + 4) = v1; } }
.LBB0_295:
	s_andn2_b64 vcc, exec, s[0:1]
	s_cbranch_vccnz .LBB0_301
	v_mov_b32_e32 v190, 0x3d372713
	v_mov_b32_e32 v192, 0xbfcc422a
	v_mov_b32_e32 v194, 0x3fb8aa3b
	v_pk_mul_f32 v[64:65], v[60:61], v[190:191] op_sel_hi:[1,0]
	v_pk_mul_f32 v[68:69], v[62:63], v[190:191] op_sel_hi:[1,0]
	v_pk_mul_f32 v[74:75], v[56:57], v[190:191] op_sel_hi:[1,0]
	v_pk_mul_f32 v[76:77], v[58:59], v[190:191] op_sel_hi:[1,0]
	v_pk_mul_f32 v[78:79], v[52:53], v[190:191] op_sel_hi:[1,0]
	v_pk_mul_f32 v[80:81], v[54:55], v[190:191] op_sel_hi:[1,0]
	v_pk_mul_f32 v[82:83], v[48:49], v[190:191] op_sel_hi:[1,0]
	v_pk_mul_f32 v[84:85], v[50:51], v[190:191] op_sel_hi:[1,0]
	v_pk_mul_f32 v[64:65], v[60:61], v[64:65]
	v_pk_mul_f32 v[68:69], v[62:63], v[68:69]
	v_pk_mul_f32 v[74:75], v[56:57], v[74:75]
	v_pk_mul_f32 v[76:77], v[58:59], v[76:77]
	v_pk_mul_f32 v[78:79], v[52:53], v[78:79]
	v_pk_mul_f32 v[80:81], v[54:55], v[80:81]
	v_pk_mul_f32 v[82:83], v[48:49], v[82:83]
	v_pk_mul_f32 v[84:85], v[50:51], v[84:85]
	v_pk_fma_f32 v[64:65], v[60:61], v[64:65], v[60:61]
	v_pk_fma_f32 v[68:69], v[62:63], v[68:69], v[62:63]
	v_pk_fma_f32 v[74:75], v[56:57], v[74:75], v[56:57]
	v_pk_fma_f32 v[76:77], v[58:59], v[76:77], v[58:59]
	v_pk_fma_f32 v[78:79], v[52:53], v[78:79], v[52:53]
	v_pk_fma_f32 v[80:81], v[54:55], v[80:81], v[54:55]
	v_pk_fma_f32 v[82:83], v[48:49], v[82:83], v[48:49]
	v_pk_fma_f32 v[84:85], v[50:51], v[84:85], v[50:51]
	v_pk_mul_f32 v[64:65], v[64:65], v[192:193] op_sel_hi:[1,0]
	v_pk_mul_f32 v[68:69], v[68:69], v[192:193] op_sel_hi:[1,0]
	v_pk_mul_f32 v[74:75], v[74:75], v[192:193] op_sel_hi:[1,0]
	v_pk_mul_f32 v[76:77], v[76:77], v[192:193] op_sel_hi:[1,0]
	v_pk_mul_f32 v[78:79], v[78:79], v[192:193] op_sel_hi:[1,0]
	v_pk_mul_f32 v[80:81], v[80:81], v[192:193] op_sel_hi:[1,0]
	v_pk_mul_f32 v[82:83], v[82:83], v[192:193] op_sel_hi:[1,0]
	v_pk_mul_f32 v[84:85], v[84:85], v[192:193] op_sel_hi:[1,0]
	v_pk_mul_f32 v[64:65], v[64:65], v[194:195] op_sel_hi:[1,0]
	v_pk_mul_f32 v[68:69], v[68:69], v[194:195] op_sel_hi:[1,0]
	v_pk_mul_f32 v[74:75], v[74:75], v[194:195] op_sel_hi:[1,0]
	v_pk_mul_f32 v[76:77], v[76:77], v[194:195] op_sel_hi:[1,0]
	v_pk_mul_f32 v[78:79], v[78:79], v[194:195] op_sel_hi:[1,0]
	v_pk_mul_f32 v[80:81], v[80:81], v[194:195] op_sel_hi:[1,0]
	v_pk_mul_f32 v[82:83], v[82:83], v[194:195] op_sel_hi:[1,0]
	v_pk_mul_f32 v[84:85], v[84:85], v[194:195] op_sel_hi:[1,0]
	v_exp_f32_e32 v64, v64
	v_exp_f32_e32 v65, v65
	v_exp_f32_e32 v68, v68
	v_exp_f32_e32 v69, v69
	v_exp_f32_e32 v74, v74
	v_exp_f32_e32 v75, v75
	v_exp_f32_e32 v76, v76
	v_exp_f32_e32 v77, v77
	v_exp_f32_e32 v78, v78
	v_exp_f32_e32 v79, v79
	v_exp_f32_e32 v80, v80
	v_exp_f32_e32 v81, v81
	v_exp_f32_e32 v82, v82
	v_exp_f32_e32 v83, v83
	v_exp_f32_e32 v84, v84
	v_exp_f32_e32 v85, v85
	v_pk_add_f32 v[64:65], v[64:65], 1.0 op_sel_hi:[1,0]
	v_pk_add_f32 v[68:69], v[68:69], 1.0 op_sel_hi:[1,0]
	v_pk_add_f32 v[74:75], v[74:75], 1.0 op_sel_hi:[1,0]
	v_pk_add_f32 v[76:77], v[76:77], 1.0 op_sel_hi:[1,0]
	v_pk_add_f32 v[78:79], v[78:79], 1.0 op_sel_hi:[1,0]
	v_pk_add_f32 v[80:81], v[80:81], 1.0 op_sel_hi:[1,0]
	v_pk_add_f32 v[82:83], v[82:83], 1.0 op_sel_hi:[1,0]
	v_pk_add_f32 v[84:85], v[84:85], 1.0 op_sel_hi:[1,0]
	v_rcp_f32_e32 v64, v64
	v_rcp_f32_e32 v65, v65
	v_rcp_f32_e32 v68, v68
	v_rcp_f32_e32 v69, v69
	v_rcp_f32_e32 v74, v74
	v_rcp_f32_e32 v75, v75
	v_rcp_f32_e32 v76, v76
	v_rcp_f32_e32 v77, v77
	v_rcp_f32_e32 v78, v78
	v_rcp_f32_e32 v79, v79
	v_rcp_f32_e32 v80, v80
	v_rcp_f32_e32 v81, v81
	v_rcp_f32_e32 v82, v82
	v_rcp_f32_e32 v83, v83
	v_rcp_f32_e32 v84, v84
	v_rcp_f32_e32 v85, v85
	v_pk_mul_f32 v[64:65], v[60:61], v[64:65]
	v_pk_mul_f32 v[68:69], v[62:63], v[68:69]
	v_pk_mul_f32 v[74:75], v[56:57], v[74:75]
	v_pk_mul_f32 v[76:77], v[58:59], v[76:77]
	v_pk_mul_f32 v[78:79], v[52:53], v[78:79]
	v_pk_mul_f32 v[80:81], v[54:55], v[80:81]
	v_pk_mul_f32 v[82:83], v[48:49], v[82:83]
	v_pk_mul_f32 v[84:85], v[50:51], v[84:85]
	v_pk_mul_f32 v[66:67], v[64:65], v[64:65]
	v_pk_mul_f32 v[70:71], v[68:69], v[68:69]
	v_add_f32_e32 v66, v66, v67
	v_add_f32_e32 v66, v70, v66
	v_pk_mul_f32 v[86:87], v[74:75], v[74:75]
	v_add_f32_e32 v66, v71, v66
	v_add_f32_e32 v66, v86, v66
	v_pk_mul_f32 v[88:89], v[76:77], v[76:77]
	v_add_f32_e32 v66, v87, v66
	v_add_f32_e32 v66, v88, v66
	v_pk_mul_f32 v[90:91], v[78:79], v[78:79]
	v_add_f32_e32 v66, v89, v66
	v_add_f32_e32 v66, v66, v90
	v_pk_mul_f32 v[92:93], v[80:81], v[80:81]
	v_add_f32_e32 v66, v91, v66
	v_add_f32_e32 v66, v92, v66
	v_pk_mul_f32 v[94:95], v[82:83], v[82:83]
	v_add_f32_e32 v66, v93, v66
	v_add_f32_e32 v66, v94, v66
	v_pk_mul_f32 v[96:97], v[84:85], v[84:85]
	v_add_f32_e32 v66, v95, v66
	v_add_f32_e32 v66, v96, v66
	v_add_f32_e32 v66, v97, v66
	v_mov_b32_e32 v67, v66
	s_nop 1
	v_permlane16_swap_b32 v66, v67
	v_lshl_add_u64 v[96:97], v[140:141], 2, s[18:19]
	v_ashrrev_i32_e32 v73, 31, v72
	v_lshlrev_b64 v[90:91], 10, v[72:73]
	v_lshlrev_b32_e32 v88, 9, v72
	s_waitcnt lgkmcnt(0)
	v_add_f32_e32 v66, v66, v67
	v_mov_b32_e32 v67, v66
	s_nop 1
	v_permlane32_swap_b32 v66, v67
	v_mov_b32_e32 v89, v141
	s_waitcnt lgkmcnt(0)
	v_add_f32_e32 v66, v66, v67
	v_fmamk_f32 v66, v66, 0x3c800000, v188
	v_cmp_gt_f32_e32 vcc, s13, v66
	v_mul_f32_e32 v67, 0x4b800000, v66
	s_nop 0
	v_cndmask_b32_e32 v66, v66, v67, vcc
	v_rsq_f32_e32 v66, v66
	s_nop 0
	v_mul_f32_e32 v67, 0x45800000, v66
	v_cndmask_b32_e32 v86, v66, v67, vcc
	v_pk_mul_f32 v[92:93], v[64:65], v[86:87] op_sel_hi:[1,0]
	v_pk_mul_f32 v[94:95], v[68:69], v[86:87] op_sel_hi:[1,0]
	v_mov_b64_e32 v[64:65], v[208:209]
	v_mov_b64_e32 v[66:67], v[210:211]
	v_mov_b64_e32 v[68:69], v[204:205]
	v_mov_b64_e32 v[70:71], v[206:207]
	v_pk_mul_f32 v[74:75], v[74:75], v[86:87] op_sel_hi:[1,0]
	v_pk_mul_f32 v[76:77], v[76:77], v[86:87] op_sel_hi:[1,0]
	v_pk_mul_f32 v[64:65], v[64:65], v[74:75]
	v_lshl_add_u64 v[74:75], s[46:47], 0, v[90:91]
	v_pk_mul_f32 v[70:71], v[70:71], v[94:95]
	v_pk_mul_f32 v[68:69], v[68:69], v[92:93]
	v_pk_mul_f32 v[66:67], v[66:67], v[76:77]
	v_lshl_add_u64 v[76:77], v[140:141], 1, v[74:75]
	v_lshl_add_u64 v[74:75], v[88:89], 2, s[56:57]
	v_cvt_pk_bf16_f32 v90, v68, v69
	v_cvt_pk_bf16_f32 v91, v70, v71
	v_cvt_pk_bf16_f32 v92, v64, v65
	v_cvt_pk_bf16_f32 v93, v66, v67
	v_mov_b64_e32 v[196:197], v[90:91]
	v_mov_b64_e32 v[198:199], v[92:93]
	s_and_saveexec_b64 s[0:1], s[10:11]
	s_cbranch_execz .LBB0_298
	v_lshl_add_u64 v[88:89], v[140:141], 2, v[74:75]
	v_lshl_add_u64 v[90:91], v[88:89], 0, s[70:71]
	v_add_co_u32_e32 v88, vcc, 0x2108000, v88
	s_nop 1
	v_addc_co_u32_e32 v89, vcc, 0, v89, vcc
	global_store_dwordx4 v[88:89], v[68:71], off
	global_store_dwordx4 v[90:91], v[64:67], off offset:16

; __device__ __forceinline__ float gelu_tanh(float x) { const float u = 1.5957691216f * (x + 0.044715f * x * x * x); return x * __builtin_amdgcn_rcpf(1.f + __expf(-u)); }
; __device__ __forceinline__ void st_bf16x8(bf16_t* p, const f32x4 a, const f32x4 b) { uint4 o; o.x = cvt_pk_bf16(a[0], a[1]); o.y = cvt_pk_bf16(a[2], a[3]); o.z = cvt_pk_bf16(b[0], b[1]); o.w = cvt_pk_bf16(b[2], b[3]); *(uint4*)p = o; }
;     __device__ __forceinline__ void row(const f32x4 (&a)[2][2], int row, int pn, int wc, int fq) const {
;     ...
;         } else if (pn < 4) {
;             const int head = (pn - 2) * 4 + wc;
;             f32x4 g[2][2]; float ss = 0.f;
; #pragma unroll
;             for (int bj = 0; bj < 2; ++bj)
; #pragma unroll
;                 for (int n = 0; n < 2; ++n)
; #pragma unroll
;                     for (int j = 0; j < 4; ++j) { const float t = gelu_tanh(a[bj][n][j]); g[bj][n][j] = t; ss += t * t; }
;             ss += __shfl_xor(ss, 16); ss += __shfl_xor(ss, 32);
;             const float rs = rsqrtf(ss * (1.f / 64.f) + EPS);
; #pragma unroll
;             for (int bj = 0; bj < 2; ++bj) { const int d = head * 64 + bj * 32 + 8 * fq;
;                 const f32x4 v0 = g[bj][0] * rs * *(const f32x4*)(g_v + d), v1 = g[bj][1] * rs * *(const f32x4*)(g_v + d + 4);
;                 st_bf16x8(pV + (size_t)row * 512 + d, v0, v1);
;                 if (row >= NP && row < NTOK) { float* o = out + O_VS + (size_t)(row - NP) * 512 + d; *(f32x4*)o = v0; *(f32x4*)(o + 4) = v1; } }
.LBB0_311:
	s_andn2_b64 vcc, exec, s[0:1]
	s_cbranch_vccnz .LBB0_317
	v_mov_b32_e32 v190, 0x3d372713
	v_mov_b32_e32 v192, 0xbfcc422a
	v_mov_b32_e32 v194, 0x3fb8aa3b
	v_pk_mul_f32 v[48:49], v[44:45], v[190:191] op_sel_hi:[1,0]
	v_pk_mul_f32 v[52:53], v[46:47], v[190:191] op_sel_hi:[1,0]
	v_pk_mul_f32 v[58:59], v[40:41], v[190:191] op_sel_hi:[1,0]
	v_pk_mul_f32 v[60:61], v[42:43], v[190:191] op_sel_hi:[1,0]
	v_pk_mul_f32 v[62:63], v[36:37], v[190:191] op_sel_hi:[1,0]
	v_pk_mul_f32 v[64:65], v[38:39], v[190:191] op_sel_hi:[1,0]
	v_pk_mul_f32 v[66:67], v[32:33], v[190:191] op_sel_hi:[1,0]
	v_pk_mul_f32 v[68:69], v[34:35], v[190:191] op_sel_hi:[1,0]
	v_pk_mul_f32 v[48:49], v[44:45], v[48:49]
	v_pk_mul_f32 v[52:53], v[46:47], v[52:53]
	v_pk_mul_f32 v[58:59], v[40:41], v[58:59]
	v_pk_mul_f32 v[60:61], v[42:43], v[60:61]
	v_pk_mul_f32 v[62:63], v[36:37], v[62:63]
	v_pk_mul_f32 v[64:65], v[38:39], v[64:65]
	v_pk_mul_f32 v[66:67], v[32:33], v[66:67]
	v_pk_mul_f32 v[68:69], v[34:35], v[68:69]
	v_pk_fma_f32 v[48:49], v[44:45], v[48:49], v[44:45]
	v_pk_fma_f32 v[52:53], v[46:47], v[52:53], v[46:47]
	v_pk_fma_f32 v[58:59], v[40:41], v[58:59], v[40:41]
	v_pk_fma_f32 v[60:61], v[42:43], v[60:61], v[42:43]
	v_pk_fma_f32 v[62:63], v[36:37], v[62:63], v[36:37]
	v_pk_fma_f32 v[64:65], v[38:39], v[64:65], v[38:39]
	v_pk_fma_f32 v[66:67], v[32:33], v[66:67], v[32:33]
	v_pk_fma_f32 v[68:69], v[34:35], v[68:69], v[34:35]
	v_pk_mul_f32 v[48:49], v[48:49], v[192:193] op_sel_hi:[1,0]
	v_pk_mul_f32 v[52:53], v[52:53], v[192:193] op_sel_hi:[1,0]
	v_pk_mul_f32 v[58:59], v[58:59], v[192:193] op_sel_hi:[1,0]
	v_pk_mul_f32 v[60:61], v[60:61], v[192:193] op_sel_hi:[1,0]
	v_pk_mul_f32 v[62:63], v[62:63], v[192:193] op_sel_hi:[1,0]
	v_pk_mul_f32 v[64:65], v[64:65], v[192:193] op_sel_hi:[1,0]
	v_pk_mul_f32 v[66:67], v[66:67], v[192:193] op_sel_hi:[1,0]
	v_pk_mul_f32 v[68:69], v[68:69], v[192:193] op_sel_hi:[1,0]
	v_pk_mul_f32 v[48:49], v[48:49], v[194:195] op_sel_hi:[1,0]
	v_pk_mul_f32 v[52:53], v[52:53], v[194:195] op_sel_hi:[1,0]
	v_pk_mul_f32 v[58:59], v[58:59], v[194:195] op_sel_hi:[1,0]
	v_pk_mul_f32 v[60:61], v[60:61], v[194:195] op_sel_hi:[1,0]
	v_pk_mul_f32 v[62:63], v[62:63], v[194:195] op_sel_hi:[1,0]
	v_pk_mul_f32 v[64:65], v[64:65], v[194:195] op_sel_hi:[1,0]
	v_pk_mul_f32 v[66:67], v[66:67], v[194:195] op_sel_hi:[1,0]
	v_pk_mul_f32 v[68:69], v[68:69], v[194:195] op_sel_hi:[1,0]
	v_exp_f32_e32 v48, v48
	v_exp_f32_e32 v49, v49
	v_exp_f32_e32 v52, v52
	v_exp_f32_e32 v53, v53
	v_exp_f32_e32 v58, v58
	v_exp_f32_e32 v59, v59
	v_exp_f32_e32 v60, v60
	v_exp_f32_e32 v61, v61
	v_exp_f32_e32 v62, v62
	v_exp_f32_e32 v63, v63
	v_exp_f32_e32 v64, v64
	v_exp_f32_e32 v65, v65
	v_exp_f32_e32 v66, v66
	v_exp_f32_e32 v67, v67
	v_exp_f32_e32 v68, v68
	v_exp_f32_e32 v69, v69
	v_pk_add_f32 v[48:49], v[48:49], 1.0 op_sel_hi:[1,0]
	v_pk_add_f32 v[52:53], v[52:53], 1.0 op_sel_hi:[1,0]
	v_pk_add_f32 v[58:59], v[58:59], 1.0 op_sel_hi:[1,0]
	v_pk_add_f32 v[60:61], v[60:61], 1.0 op_sel_hi:[1,0]
	v_pk_add_f32 v[62:63], v[62:63], 1.0 op_sel_hi:[1,0]
	v_pk_add_f32 v[64:65], v[64:65], 1.0 op_sel_hi:[1,0]
	v_pk_add_f32 v[66:67], v[66:67], 1.0 op_sel_hi:[1,0]
	v_pk_add_f32 v[68:69], v[68:69], 1.0 op_sel_hi:[1,0]
	v_rcp_f32_e32 v48, v48
	v_rcp_f32_e32 v49, v49
	v_rcp_f32_e32 v52, v52
	v_rcp_f32_e32 v53, v53
	v_rcp_f32_e32 v58, v58
	v_rcp_f32_e32 v59, v59
	v_rcp_f32_e32 v60, v60
	v_rcp_f32_e32 v61, v61
	v_rcp_f32_e32 v62, v62
	v_rcp_f32_e32 v63, v63
	v_rcp_f32_e32 v64, v64
	v_rcp_f32_e32 v65, v65
	v_rcp_f32_e32 v66, v66
	v_rcp_f32_e32 v67, v67
	v_rcp_f32_e32 v68, v68
	v_rcp_f32_e32 v69, v69
	v_pk_mul_f32 v[48:49], v[44:45], v[48:49]
	v_pk_mul_f32 v[52:53], v[46:47], v[52:53]
	v_pk_mul_f32 v[58:59], v[40:41], v[58:59]
	v_pk_mul_f32 v[60:61], v[42:43], v[60:61]
	v_pk_mul_f32 v[62:63], v[36:37], v[62:63]
	v_pk_mul_f32 v[64:65], v[38:39], v[64:65]
	v_pk_mul_f32 v[66:67], v[32:33], v[66:67]
	v_pk_mul_f32 v[68:69], v[34:35], v[68:69]
	v_pk_mul_f32 v[50:51], v[48:49], v[48:49]
	v_pk_mul_f32 v[54:55], v[52:53], v[52:53]
	v_add_f32_e32 v50, v50, v51
	v_add_f32_e32 v50, v54, v50
	v_pk_mul_f32 v[70:71], v[58:59], v[58:59]
	v_add_f32_e32 v50, v55, v50
	v_add_f32_e32 v50, v70, v50
	v_pk_mul_f32 v[74:75], v[60:61], v[60:61]
	v_add_f32_e32 v50, v71, v50
	v_add_f32_e32 v50, v74, v50
	v_pk_mul_f32 v[76:77], v[62:63], v[62:63]
	v_add_f32_e32 v50, v75, v50
	v_add_f32_e32 v50, v50, v76
	v_pk_mul_f32 v[78:79], v[64:65], v[64:65]
	v_add_f32_e32 v50, v77, v50
	v_add_f32_e32 v50, v78, v50
	v_pk_mul_f32 v[80:81], v[66:67], v[66:67]
	v_add_f32_e32 v50, v79, v50
	v_add_f32_e32 v50, v80, v50
	v_pk_mul_f32 v[82:83], v[68:69], v[68:69]
	v_add_f32_e32 v50, v81, v50
	v_add_f32_e32 v50, v82, v50
	v_add_f32_e32 v50, v83, v50
	v_mov_b32_e32 v51, v50
	s_nop 1
	v_permlane16_swap_b32 v50, v51
	v_lshl_add_u64 v[82:83], v[140:141], 2, s[18:19]
	v_ashrrev_i32_e32 v57, 31, v56
	v_lshlrev_b64 v[76:77], 10, v[56:57]
	v_lshlrev_b32_e32 v74, 9, v56
	s_waitcnt lgkmcnt(0)
	v_add_f32_e32 v50, v50, v51
	v_mov_b32_e32 v51, v50
	s_nop 1
	v_permlane32_swap_b32 v50, v51
	v_mov_b32_e32 v75, v141
	s_waitcnt lgkmcnt(0)
	v_add_f32_e32 v50, v50, v51
	v_fmamk_f32 v50, v50, 0x3c800000, v188
	v_cmp_gt_f32_e32 vcc, s13, v50
	v_mul_f32_e32 v51, 0x4b800000, v50
	s_nop 0
	v_cndmask_b32_e32 v50, v50, v51, vcc
	v_rsq_f32_e32 v50, v50
	s_nop 0
	v_mul_f32_e32 v51, 0x45800000, v50
	v_cndmask_b32_e32 v70, v50, v51, vcc
	v_pk_mul_f32 v[78:79], v[48:49], v[70:71] op_sel_hi:[1,0]
	v_pk_mul_f32 v[80:81], v[52:53], v[70:71] op_sel_hi:[1,0]
	v_mov_b64_e32 v[48:49], v[208:209]
	v_mov_b64_e32 v[50:51], v[210:211]
	v_mov_b64_e32 v[52:53], v[204:205]
	v_mov_b64_e32 v[54:55], v[206:207]
	v_pk_mul_f32 v[58:59], v[58:59], v[70:71] op_sel_hi:[1,0]
	v_pk_mul_f32 v[60:61], v[60:61], v[70:71] op_sel_hi:[1,0]
	v_pk_mul_f32 v[48:49], v[48:49], v[58:59]
	v_lshl_add_u64 v[58:59], s[46:47], 0, v[76:77]
	v_pk_mul_f32 v[54:55], v[54:55], v[80:81]
	v_pk_mul_f32 v[52:53], v[52:53], v[78:79]
	v_pk_mul_f32 v[50:51], v[50:51], v[60:61]
	v_lshl_add_u64 v[60:61], v[140:141], 1, v[58:59]
	v_lshl_add_u64 v[58:59], v[74:75], 2, s[56:57]
	v_cvt_pk_bf16_f32 v76, v52, v53
	v_cvt_pk_bf16_f32 v77, v54, v55
	v_cvt_pk_bf16_f32 v78, v48, v49
	v_cvt_pk_bf16_f32 v79, v50, v51
	v_mov_b64_e32 v[196:197], v[76:77]
	v_mov_b64_e32 v[198:199], v[78:79]
	s_and_saveexec_b64 s[0:1], s[10:11]
	s_cbranch_execz .LBB0_314
	v_lshl_add_u64 v[74:75], v[140:141], 2, v[58:59]
	v_lshl_add_u64 v[76:77], v[74:75], 0, s[70:71]
	v_add_co_u32_e32 v74, vcc, 0x2108000, v74
	s_nop 1
	v_addc_co_u32_e32 v75, vcc, 0, v75, vcc
	global_store_dwordx4 v[74:75], v[52:55], off
	global_store_dwordx4 v[76:77], v[48:51], off offset:16

; __device__ __forceinline__ float gelu_tanh(float x) { const float u = 1.5957691216f * (x + 0.044715f * x * x * x); return x * __builtin_amdgcn_rcpf(1.f + __expf(-u)); }
; __device__ __forceinline__ void st_bf16x8(bf16_t* p, const f32x4 a, const f32x4 b) { uint4 o; o.x = cvt_pk_bf16(a[0], a[1]); o.y = cvt_pk_bf16(a[2], a[3]); o.z = cvt_pk_bf16(b[0], b[1]); o.w = cvt_pk_bf16(b[2], b[3]); *(uint4*)p = o; }
;     __device__ __forceinline__ void row(const f32x4 (&a)[2][2], int row, int pn, int wc, int fq) const {
;     ...
;         } else if (pn < 4) {
;             const int head = (pn - 2) * 4 + wc;
;             f32x4 g[2][2]; float ss = 0.f;
; #pragma unroll
;             for (int bj = 0; bj < 2; ++bj)
; #pragma unroll
;                 for (int n = 0; n < 2; ++n)
; #pragma unroll
;                     for (int j = 0; j < 4; ++j) { const float t = gelu_tanh(a[bj][n][j]); g[bj][n][j] = t; ss += t * t; }
;             ss += __shfl_xor(ss, 16); ss += __shfl_xor(ss, 32);
;             const float rs = rsqrtf(ss * (1.f / 64.f) + EPS);
; #pragma unroll
;             for (int bj = 0; bj < 2; ++bj) { const int d = head * 64 + bj * 32 + 8 * fq;
;                 const f32x4 v0 = g[bj][0] * rs * *(const f32x4*)(g_v + d), v1 = g[bj][1] * rs * *(const f32x4*)(g_v + d + 4);
;                 st_bf16x8(pV + (size_t)row * 512 + d, v0, v1);
;                 if (row >= NP && row < NTOK) { float* o = out + O_VS + (size_t)(row - NP) * 512 + d; *(f32x4*)o = v0; *(f32x4*)(o + 4) = v1; } }
.LBB0_327:
	s_andn2_b64 vcc, exec, s[0:1]
	s_cbranch_vccnz .LBB0_333
	v_mov_b32_e32 v190, 0x3d372713
	v_mov_b32_e32 v192, 0xbfcc422a
	v_mov_b32_e32 v194, 0x3fb8aa3b
	v_pk_mul_f32 v[32:33], v[28:29], v[190:191] op_sel_hi:[1,0]
	v_pk_mul_f32 v[36:37], v[30:31], v[190:191] op_sel_hi:[1,0]
	v_pk_mul_f32 v[42:43], v[24:25], v[190:191] op_sel_hi:[1,0]
	v_pk_mul_f32 v[44:45], v[26:27], v[190:191] op_sel_hi:[1,0]
	v_pk_mul_f32 v[46:47], v[20:21], v[190:191] op_sel_hi:[1,0]
	v_pk_mul_f32 v[48:49], v[22:23], v[190:191] op_sel_hi:[1,0]
	v_pk_mul_f32 v[50:51], v[16:17], v[190:191] op_sel_hi:[1,0]
	v_pk_mul_f32 v[52:53], v[18:19], v[190:191] op_sel_hi:[1,0]
	v_pk_mul_f32 v[32:33], v[28:29], v[32:33]
	v_pk_mul_f32 v[36:37], v[30:31], v[36:37]
	v_pk_mul_f32 v[42:43], v[24:25], v[42:43]
	v_pk_mul_f32 v[44:45], v[26:27], v[44:45]
	v_pk_mul_f32 v[46:47], v[20:21], v[46:47]
	v_pk_mul_f32 v[48:49], v[22:23], v[48:49]
	v_pk_mul_f32 v[50:51], v[16:17], v[50:51]
	v_pk_mul_f32 v[52:53], v[18:19], v[52:53]
	v_pk_fma_f32 v[32:33], v[28:29], v[32:33], v[28:29]
	v_pk_fma_f32 v[36:37], v[30:31], v[36:37], v[30:31]
	v_pk_fma_f32 v[42:43], v[24:25], v[42:43], v[24:25]
	v_pk_fma_f32 v[44:45], v[26:27], v[44:45], v[26:27]
	v_pk_fma_f32 v[46:47], v[20:21], v[46:47], v[20:21]
	v_pk_fma_f32 v[48:49], v[22:23], v[48:49], v[22:23]
	v_pk_fma_f32 v[50:51], v[16:17], v[50:51], v[16:17]
	v_pk_fma_f32 v[52:53], v[18:19], v[52:53], v[18:19]
	v_pk_mul_f32 v[32:33], v[32:33], v[192:193] op_sel_hi:[1,0]
	v_pk_mul_f32 v[36:37], v[36:37], v[192:193] op_sel_hi:[1,0]
	v_pk_mul_f32 v[42:43], v[42:43], v[192:193] op_sel_hi:[1,0]
	v_pk_mul_f32 v[44:45], v[44:45], v[192:193] op_sel_hi:[1,0]
	v_pk_mul_f32 v[46:47], v[46:47], v[192:193] op_sel_hi:[1,0]
	v_pk_mul_f32 v[48:49], v[48:49], v[192:193] op_sel_hi:[1,0]
	v_pk_mul_f32 v[50:51], v[50:51], v[192:193] op_sel_hi:[1,0]
	v_pk_mul_f32 v[52:53], v[52:53], v[192:193] op_sel_hi:[1,0]
	v_pk_mul_f32 v[32:33], v[32:33], v[194:195] op_sel_hi:[1,0]
	v_pk_mul_f32 v[36:37], v[36:37], v[194:195] op_sel_hi:[1,0]
	v_pk_mul_f32 v[42:43], v[42:43], v[194:195] op_sel_hi:[1,0]
	v_pk_mul_f32 v[44:45], v[44:45], v[194:195] op_sel_hi:[1,0]
	v_pk_mul_f32 v[46:47], v[46:47], v[194:195] op_sel_hi:[1,0]
	v_pk_mul_f32 v[48:49], v[48:49], v[194:195] op_sel_hi:[1,0]
	v_pk_mul_f32 v[50:51], v[50:51], v[194:195] op_sel_hi:[1,0]
	v_pk_mul_f32 v[52:53], v[52:53], v[194:195] op_sel_hi:[1,0]
	v_exp_f32_e32 v32, v32
	v_exp_f32_e32 v33, v33
	v_exp_f32_e32 v36, v36
	v_exp_f32_e32 v37, v37
	v_exp_f32_e32 v42, v42
	v_exp_f32_e32 v43, v43
	v_exp_f32_e32 v44, v44
	v_exp_f32_e32 v45, v45
	v_exp_f32_e32 v46, v46
	v_exp_f32_e32 v47, v47
	v_exp_f32_e32 v48, v48
	v_exp_f32_e32 v49, v49
	v_exp_f32_e32 v50, v50
	v_exp_f32_e32 v51, v51
	v_exp_f32_e32 v52, v52
	v_exp_f32_e32 v53, v53
	v_pk_add_f32 v[32:33], v[32:33], 1.0 op_sel_hi:[1,0]
	v_pk_add_f32 v[36:37], v[36:37], 1.0 op_sel_hi:[1,0]
	v_pk_add_f32 v[42:43], v[42:43], 1.0 op_sel_hi:[1,0]
	v_pk_add_f32 v[44:45], v[44:45], 1.0 op_sel_hi:[1,0]
	v_pk_add_f32 v[46:47], v[46:47], 1.0 op_sel_hi:[1,0]
	v_pk_add_f32 v[48:49], v[48:49], 1.0 op_sel_hi:[1,0]
	v_pk_add_f32 v[50:51], v[50:51], 1.0 op_sel_hi:[1,0]
	v_pk_add_f32 v[52:53], v[52:53], 1.0 op_sel_hi:[1,0]
	v_rcp_f32_e32 v32, v32
	v_rcp_f32_e32 v33, v33
	v_rcp_f32_e32 v36, v36
	v_rcp_f32_e32 v37, v37
	v_rcp_f32_e32 v42, v42
	v_rcp_f32_e32 v43, v43
	v_rcp_f32_e32 v44, v44
	v_rcp_f32_e32 v45, v45
	v_rcp_f32_e32 v46, v46
	v_rcp_f32_e32 v47, v47
	v_rcp_f32_e32 v48, v48
	v_rcp_f32_e32 v49, v49
	v_rcp_f32_e32 v50, v50
	v_rcp_f32_e32 v51, v51
	v_rcp_f32_e32 v52, v52
	v_rcp_f32_e32 v53, v53
	v_pk_mul_f32 v[32:33], v[28:29], v[32:33]
	v_pk_mul_f32 v[36:37], v[30:31], v[36:37]
	v_pk_mul_f32 v[42:43], v[24:25], v[42:43]
	v_pk_mul_f32 v[44:45], v[26:27], v[44:45]
	v_pk_mul_f32 v[46:47], v[20:21], v[46:47]
	v_pk_mul_f32 v[48:49], v[22:23], v[48:49]
	v_pk_mul_f32 v[50:51], v[16:17], v[50:51]
	v_pk_mul_f32 v[52:53], v[18:19], v[52:53]
	v_pk_mul_f32 v[34:35], v[32:33], v[32:33]
	v_pk_mul_f32 v[38:39], v[36:37], v[36:37]
	v_add_f32_e32 v34, v34, v35
	v_add_f32_e32 v34, v38, v34
	v_pk_mul_f32 v[54:55], v[42:43], v[42:43]
	v_add_f32_e32 v34, v39, v34
	v_add_f32_e32 v34, v54, v34
	v_pk_mul_f32 v[56:57], v[44:45], v[44:45]
	v_add_f32_e32 v34, v55, v34
	v_add_f32_e32 v34, v56, v34
	v_pk_mul_f32 v[58:59], v[46:47], v[46:47]
	v_add_f32_e32 v34, v57, v34
	v_add_f32_e32 v34, v34, v58
	v_pk_mul_f32 v[60:61], v[48:49], v[48:49]
	v_add_f32_e32 v34, v59, v34
	v_add_f32_e32 v34, v60, v34
	v_pk_mul_f32 v[62:63], v[50:51], v[50:51]
	v_add_f32_e32 v34, v61, v34
	v_add_f32_e32 v34, v62, v34
	v_pk_mul_f32 v[64:65], v[52:53], v[52:53]
	v_add_f32_e32 v34, v63, v34
	v_add_f32_e32 v34, v64, v34
	v_add_f32_e32 v34, v65, v34
	v_mov_b32_e32 v35, v34
	s_nop 1
	v_permlane16_swap_b32 v34, v35
	v_lshl_add_u64 v[64:65], v[140:141], 2, s[18:19]
	v_ashrrev_i32_e32 v41, 31, v40
	v_lshlrev_b64 v[58:59], 10, v[40:41]
	v_lshlrev_b32_e32 v56, 9, v40
	s_waitcnt lgkmcnt(0)
	v_add_f32_e32 v34, v34, v35
	v_mov_b32_e32 v35, v34
	s_nop 1
	v_permlane32_swap_b32 v34, v35
	v_mov_b32_e32 v57, v141
	s_waitcnt lgkmcnt(0)
	v_add_f32_e32 v34, v34, v35
	v_fmamk_f32 v34, v34, 0x3c800000, v188
	v_cmp_gt_f32_e32 vcc, s13, v34
	v_mul_f32_e32 v35, 0x4b800000, v34
	s_nop 0
	v_cndmask_b32_e32 v34, v34, v35, vcc
	v_rsq_f32_e32 v34, v34
	s_nop 0
	v_mul_f32_e32 v35, 0x45800000, v34
	v_cndmask_b32_e32 v54, v34, v35, vcc
	v_pk_mul_f32 v[60:61], v[32:33], v[54:55] op_sel_hi:[1,0]
	v_pk_mul_f32 v[62:63], v[36:37], v[54:55] op_sel_hi:[1,0]
	v_mov_b64_e32 v[32:33], v[208:209]
	v_mov_b64_e32 v[34:35], v[210:211]
	v_mov_b64_e32 v[36:37], v[204:205]
	v_mov_b64_e32 v[38:39], v[206:207]
	v_pk_mul_f32 v[42:43], v[42:43], v[54:55] op_sel_hi:[1,0]
	v_pk_mul_f32 v[44:45], v[44:45], v[54:55] op_sel_hi:[1,0]
	v_pk_mul_f32 v[32:33], v[32:33], v[42:43]
	v_lshl_add_u64 v[42:43], s[46:47], 0, v[58:59]
	v_pk_mul_f32 v[38:39], v[38:39], v[62:63]
	v_pk_mul_f32 v[36:37], v[36:37], v[60:61]
	v_pk_mul_f32 v[34:35], v[34:35], v[44:45]
	v_lshl_add_u64 v[44:45], v[140:141], 1, v[42:43]
	v_lshl_add_u64 v[42:43], v[56:57], 2, s[56:57]
	v_cvt_pk_bf16_f32 v58, v36, v37
	v_cvt_pk_bf16_f32 v59, v38, v39
	v_cvt_pk_bf16_f32 v60, v32, v33
	v_cvt_pk_bf16_f32 v61, v34, v35
	v_mov_b64_e32 v[196:197], v[58:59]
	v_mov_b64_e32 v[198:199], v[60:61]
	s_and_saveexec_b64 s[0:1], s[10:11]
	s_cbranch_execz .LBB0_330
	v_lshl_add_u64 v[56:57], v[140:141], 2, v[42:43]
	v_lshl_add_u64 v[58:59], v[56:57], 0, s[70:71]
	v_add_co_u32_e32 v56, vcc, 0x2108000, v56
	s_nop 1
	v_addc_co_u32_e32 v57, vcc, 0, v57, vcc
	global_store_dwordx4 v[56:57], v[36:39], off
	global_store_dwordx4 v[58:59], v[32:35], off offset:16

; __device__ __forceinline__ float gelu_tanh(float x) { const float u = 1.5957691216f * (x + 0.044715f * x * x * x); return x * __builtin_amdgcn_rcpf(1.f + __expf(-u)); }
; __device__ __forceinline__ void st_bf16x8(bf16_t* p, const f32x4 a, const f32x4 b) { uint4 o; o.x = cvt_pk_bf16(a[0], a[1]); o.y = cvt_pk_bf16(a[2], a[3]); o.z = cvt_pk_bf16(b[0], b[1]); o.w = cvt_pk_bf16(b[2], b[3]); *(uint4*)p = o; }
;     __device__ __forceinline__ void row(const f32x4 (&a)[2][2], int row, int pn, int wc, int fq) const {
;     ...
;         } else if (pn < 4) {
;             const int head = (pn - 2) * 4 + wc;
;             f32x4 g[2][2]; float ss = 0.f;
; #pragma unroll
;             for (int bj = 0; bj < 2; ++bj)
; #pragma unroll
;                 for (int n = 0; n < 2; ++n)
; #pragma unroll
;                     for (int j = 0; j < 4; ++j) { const float t = gelu_tanh(a[bj][n][j]); g[bj][n][j] = t; ss += t * t; }
;             ss += __shfl_xor(ss, 16); ss += __shfl_xor(ss, 32);
;             const float rs = rsqrtf(ss * (1.f / 64.f) + EPS);
; #pragma unroll
;             for (int bj = 0; bj < 2; ++bj) { const int d = head * 64 + bj * 32 + 8 * fq;
;                 const f32x4 v0 = g[bj][0] * rs * *(const f32x4*)(g_v + d), v1 = g[bj][1] * rs * *(const f32x4*)(g_v + d + 4);
;                 st_bf16x8(pV + (size_t)row * 512 + d, v0, v1);
;                 if (row >= NP && row < NTOK) { float* o = out + O_VS + (size_t)(row - NP) * 512 + d; *(f32x4*)o = v0; *(f32x4*)(o + 4) = v1; } }
.LBB0_345:
	s_and_b64 vcc, exec, s[0:1]
	s_cbranch_vccz .LBB0_351
	v_mov_b32_e32 v190, 0x3d372713
	v_mov_b32_e32 v192, 0xbfcc422a
	v_mov_b32_e32 v194, 0x3fb8aa3b
	v_pk_mul_f32 v[16:17], v[12:13], v[190:191] op_sel_hi:[1,0]
	v_pk_mul_f32 v[20:21], v[14:15], v[190:191] op_sel_hi:[1,0]
	v_pk_mul_f32 v[26:27], v[8:9], v[190:191] op_sel_hi:[1,0]
	v_pk_mul_f32 v[28:29], v[10:11], v[190:191] op_sel_hi:[1,0]
	v_pk_mul_f32 v[30:31], v[4:5], v[190:191] op_sel_hi:[1,0]
	v_pk_mul_f32 v[32:33], v[6:7], v[190:191] op_sel_hi:[1,0]
	v_pk_mul_f32 v[34:35], v[0:1], v[190:191] op_sel_hi:[1,0]
	v_pk_mul_f32 v[36:37], v[2:3], v[190:191] op_sel_hi:[1,0]
	v_pk_mul_f32 v[16:17], v[12:13], v[16:17]
	v_pk_mul_f32 v[20:21], v[14:15], v[20:21]
	v_pk_mul_f32 v[26:27], v[8:9], v[26:27]
	v_pk_mul_f32 v[28:29], v[10:11], v[28:29]
	v_pk_mul_f32 v[30:31], v[4:5], v[30:31]
	v_pk_mul_f32 v[32:33], v[6:7], v[32:33]
	v_pk_mul_f32 v[34:35], v[0:1], v[34:35]
	v_pk_mul_f32 v[36:37], v[2:3], v[36:37]
	v_pk_fma_f32 v[16:17], v[12:13], v[16:17], v[12:13]
	v_pk_fma_f32 v[20:21], v[14:15], v[20:21], v[14:15]
	v_pk_fma_f32 v[26:27], v[8:9], v[26:27], v[8:9]
	v_pk_fma_f32 v[28:29], v[10:11], v[28:29], v[10:11]
	v_pk_fma_f32 v[30:31], v[4:5], v[30:31], v[4:5]
	v_pk_fma_f32 v[32:33], v[6:7], v[32:33], v[6:7]
	v_pk_fma_f32 v[34:35], v[0:1], v[34:35], v[0:1]
	v_pk_fma_f32 v[36:37], v[2:3], v[36:37], v[2:3]
	v_pk_mul_f32 v[16:17], v[16:17], v[192:193] op_sel_hi:[1,0]
	v_pk_mul_f32 v[20:21], v[20:21], v[192:193] op_sel_hi:[1,0]
	v_pk_mul_f32 v[26:27], v[26:27], v[192:193] op_sel_hi:[1,0]
	v_pk_mul_f32 v[28:29], v[28:29], v[192:193] op_sel_hi:[1,0]
	v_pk_mul_f32 v[30:31], v[30:31], v[192:193] op_sel_hi:[1,0]
	v_pk_mul_f32 v[32:33], v[32:33], v[192:193] op_sel_hi:[1,0]
	v_pk_mul_f32 v[34:35], v[34:35], v[192:193] op_sel_hi:[1,0]
	v_pk_mul_f32 v[36:37], v[36:37], v[192:193] op_sel_hi:[1,0]
	v_pk_mul_f32 v[16:17], v[16:17], v[194:195] op_sel_hi:[1,0]
	v_pk_mul_f32 v[20:21], v[20:21], v[194:195] op_sel_hi:[1,0]
	v_pk_mul_f32 v[26:27], v[26:27], v[194:195] op_sel_hi:[1,0]
	v_pk_mul_f32 v[28:29], v[28:29], v[194:195] op_sel_hi:[1,0]
	v_pk_mul_f32 v[30:31], v[30:31], v[194:195] op_sel_hi:[1,0]
	v_pk_mul_f32 v[32:33], v[32:33], v[194:195] op_sel_hi:[1,0]
	v_pk_mul_f32 v[34:35], v[34:35], v[194:195] op_sel_hi:[1,0]
	v_pk_mul_f32 v[36:37], v[36:37], v[194:195] op_sel_hi:[1,0]
	v_exp_f32_e32 v16, v16
	v_exp_f32_e32 v17, v17
	v_exp_f32_e32 v20, v20
	v_exp_f32_e32 v21, v21
	v_exp_f32_e32 v26, v26
	v_exp_f32_e32 v27, v27
	v_exp_f32_e32 v28, v28
	v_exp_f32_e32 v29, v29
	v_exp_f32_e32 v30, v30
	v_exp_f32_e32 v31, v31
	v_exp_f32_e32 v32, v32
	v_exp_f32_e32 v33, v33
	v_exp_f32_e32 v34, v34
	v_exp_f32_e32 v35, v35
	v_exp_f32_e32 v36, v36
	v_exp_f32_e32 v37, v37
	v_pk_add_f32 v[16:17], v[16:17], 1.0 op_sel_hi:[1,0]
	v_pk_add_f32 v[20:21], v[20:21], 1.0 op_sel_hi:[1,0]
	v_pk_add_f32 v[26:27], v[26:27], 1.0 op_sel_hi:[1,0]
	v_pk_add_f32 v[28:29], v[28:29], 1.0 op_sel_hi:[1,0]
	v_pk_add_f32 v[30:31], v[30:31], 1.0 op_sel_hi:[1,0]
	v_pk_add_f32 v[32:33], v[32:33], 1.0 op_sel_hi:[1,0]
	v_pk_add_f32 v[34:35], v[34:35], 1.0 op_sel_hi:[1,0]
	v_pk_add_f32 v[36:37], v[36:37], 1.0 op_sel_hi:[1,0]
	v_rcp_f32_e32 v16, v16
	v_rcp_f32_e32 v17, v17
	v_rcp_f32_e32 v20, v20
	v_rcp_f32_e32 v21, v21
	v_rcp_f32_e32 v26, v26
	v_rcp_f32_e32 v27, v27
	v_rcp_f32_e32 v28, v28
	v_rcp_f32_e32 v29, v29
	v_rcp_f32_e32 v30, v30
	v_rcp_f32_e32 v31, v31
	v_rcp_f32_e32 v32, v32
	v_rcp_f32_e32 v33, v33
	v_rcp_f32_e32 v34, v34
	v_rcp_f32_e32 v35, v35
	v_rcp_f32_e32 v36, v36
	v_rcp_f32_e32 v37, v37
	v_pk_mul_f32 v[16:17], v[12:13], v[16:17]
	v_pk_mul_f32 v[20:21], v[14:15], v[20:21]
	v_pk_mul_f32 v[26:27], v[8:9], v[26:27]
	v_pk_mul_f32 v[28:29], v[10:11], v[28:29]
	v_pk_mul_f32 v[30:31], v[4:5], v[30:31]
	v_pk_mul_f32 v[32:33], v[6:7], v[32:33]
	v_pk_mul_f32 v[34:35], v[0:1], v[34:35]
	v_pk_mul_f32 v[36:37], v[2:3], v[36:37]
	v_pk_mul_f32 v[18:19], v[16:17], v[16:17]
	v_pk_mul_f32 v[22:23], v[20:21], v[20:21]
	v_add_f32_e32 v18, v18, v19
	v_add_f32_e32 v18, v22, v18
	v_pk_mul_f32 v[38:39], v[26:27], v[26:27]
	v_add_f32_e32 v18, v23, v18
	v_add_f32_e32 v18, v38, v18
	v_pk_mul_f32 v[40:41], v[28:29], v[28:29]
	v_add_f32_e32 v18, v39, v18
	v_add_f32_e32 v18, v40, v18
	v_pk_mul_f32 v[42:43], v[30:31], v[30:31]
	v_add_f32_e32 v18, v41, v18
	v_add_f32_e32 v18, v18, v42
	v_pk_mul_f32 v[44:45], v[32:33], v[32:33]
	v_add_f32_e32 v18, v43, v18
	v_add_f32_e32 v18, v44, v18
	v_pk_mul_f32 v[46:47], v[34:35], v[34:35]
	v_add_f32_e32 v18, v45, v18
	v_add_f32_e32 v18, v46, v18
	v_pk_mul_f32 v[48:49], v[36:37], v[36:37]
	v_add_f32_e32 v18, v47, v18
	v_add_f32_e32 v18, v48, v18
	v_add_f32_e32 v18, v49, v18
	v_mov_b32_e32 v19, v18
	s_nop 1
	v_permlane16_swap_b32 v18, v19
	v_lshl_add_u64 v[48:49], v[140:141], 2, s[18:19]
	v_ashrrev_i32_e32 v25, 31, v24
	v_lshlrev_b64 v[42:43], 10, v[24:25]
	v_lshlrev_b32_e32 v40, 9, v24
	s_waitcnt lgkmcnt(0)
	v_add_f32_e32 v18, v18, v19
	v_mov_b32_e32 v19, v18
	s_nop 1
	v_permlane32_swap_b32 v18, v19
	v_mov_b32_e32 v41, v141
	s_waitcnt lgkmcnt(0)
	v_add_f32_e32 v18, v18, v19
	v_fmamk_f32 v18, v18, 0x3c800000, v188
	v_cmp_gt_f32_e32 vcc, s13, v18
	v_mul_f32_e32 v19, 0x4b800000, v18
	s_nop 0
	v_cndmask_b32_e32 v18, v18, v19, vcc
	v_rsq_f32_e32 v18, v18
	s_nop 0
	v_mul_f32_e32 v19, 0x45800000, v18
	v_cndmask_b32_e32 v38, v18, v19, vcc
	v_pk_mul_f32 v[44:45], v[16:17], v[38:39] op_sel_hi:[1,0]
	v_pk_mul_f32 v[46:47], v[20:21], v[38:39] op_sel_hi:[1,0]
	v_mov_b64_e32 v[16:17], v[208:209]
	v_mov_b64_e32 v[18:19], v[210:211]
	v_mov_b64_e32 v[20:21], v[204:205]
	v_mov_b64_e32 v[22:23], v[206:207]
	v_pk_mul_f32 v[26:27], v[26:27], v[38:39] op_sel_hi:[1,0]
	v_pk_mul_f32 v[28:29], v[28:29], v[38:39] op_sel_hi:[1,0]
	v_pk_mul_f32 v[16:17], v[16:17], v[26:27]
	v_lshl_add_u64 v[26:27], s[46:47], 0, v[42:43]
	v_pk_mul_f32 v[22:23], v[22:23], v[46:47]
	v_pk_mul_f32 v[20:21], v[20:21], v[44:45]
	v_pk_mul_f32 v[18:19], v[18:19], v[28:29]
	v_lshl_add_u64 v[28:29], v[140:141], 1, v[26:27]
	v_lshl_add_u64 v[26:27], v[40:41], 2, s[56:57]
	v_cvt_pk_bf16_f32 v42, v20, v21
	v_cvt_pk_bf16_f32 v43, v22, v23
	v_cvt_pk_bf16_f32 v44, v16, v17
	v_cvt_pk_bf16_f32 v45, v18, v19
	v_mov_b64_e32 v[196:197], v[42:43]
	v_mov_b64_e32 v[198:199], v[44:45]
	s_and_saveexec_b64 s[0:1], s[10:11]
	s_cbranch_execz .LBB0_348
	v_lshl_add_u64 v[40:41], v[140:141], 2, v[26:27]
	v_lshl_add_u64 v[42:43], v[40:41], 0, s[70:71]
	v_add_co_u32_e32 v40, vcc, 0x2108000, v40
	s_nop 1
	v_addc_co_u32_e32 v41, vcc, 0, v41, vcc
	global_store_dwordx4 v[40:41], v[20:23], off
	global_store_dwordx4 v[42:43], v[16:19], off offset:16
